# LN1/router token loop: w_group per-lane values resident in VGPRs (loaded once per 64-token item), ln1 gamma/beta staged once per phase in free LDS and read by ds_read_b128; no constant global loads le
# speedup vs baseline: 1.0257x; 1.0112x over previous
.LBB0_545:
	s_or_b64 exec, exec, s[0:1]
	s_waitcnt vmcnt(1)
	v_mov_b32_e32 v56, v128
	s_waitcnt lgkmcnt(0)
	s_barrier
	s_nop 0
	v_add_u32_e32 v66, 0x100, v56
	v_ashrrev_i32_e32 v57, 31, v56
	v_ashrrev_i32_e32 v67, 31, v66
	v_lshl_add_u64 v[0:1], v[56:57], 4, s[70:71]
	v_lshl_add_u64 v[4:5], v[66:67], 4, s[70:71]
	v_add_u32_e32 v68, 0x200, v56
	v_add_u32_e32 v70, 0x300, v56
	s_barrier
	global_load_dwordx4 v[0:3], v[0:1], off
	s_nop 0
	global_load_dwordx4 v[4:7], v[4:5], off
	v_ashrrev_i32_e32 v69, 31, v68
	v_ashrrev_i32_e32 v71, 31, v70
	v_lshl_add_u64 v[8:9], v[68:69], 4, s[70:71]
	v_lshl_add_u64 v[12:13], v[70:71], 4, s[70:71]
	v_add_u32_e32 v72, 0x400, v56
	global_load_dwordx4 v[8:11], v[8:9], off
	v_ashrrev_i32_e32 v73, 31, v72
	global_load_dwordx4 v[12:15], v[12:13], off
	v_lshl_add_u64 v[16:17], v[72:73], 4, s[70:71]
	v_add_u32_e32 v74, 0x500, v56
	global_load_dwordx4 v[16:19], v[16:17], off
	v_ashrrev_i32_e32 v75, 31, v74
	v_lshl_add_u64 v[20:21], v[74:75], 4, s[70:71]
	v_add_u32_e32 v76, 0x600, v56
	global_load_dwordx4 v[20:23], v[20:21], off
	v_ashrrev_i32_e32 v77, 31, v76
	v_lshl_add_u64 v[24:25], v[76:77], 4, s[70:71]
	v_add_u32_e32 v78, 0x700, v56
	global_load_dwordx4 v[24:27], v[24:25], off
	v_ashrrev_i32_e32 v79, 31, v78
	v_lshl_add_u64 v[28:29], v[78:79], 4, s[70:71]
	v_add_u32_e32 v80, 0x800, v56
	global_load_dwordx4 v[28:31], v[28:29], off
	v_ashrrev_i32_e32 v81, 31, v80
	v_lshl_add_u64 v[32:33], v[80:81], 4, s[70:71]
	v_add_u32_e32 v82, 0x900, v56
	global_load_dwordx4 v[32:35], v[32:33], off
	v_ashrrev_i32_e32 v83, 31, v82
	v_lshl_add_u64 v[36:37], v[82:83], 4, s[70:71]
	v_add_u32_e32 v84, 0xa00, v56
	global_load_dwordx4 v[36:39], v[36:37], off
	v_ashrrev_i32_e32 v85, 31, v84
	v_lshl_add_u64 v[40:41], v[84:85], 4, s[70:71]
	v_add_u32_e32 v86, 0xb00, v56
	global_load_dwordx4 v[40:43], v[40:41], off
	v_ashrrev_i32_e32 v87, 31, v86
	v_lshl_add_u64 v[44:45], v[86:87], 4, s[70:71]
	v_add_u32_e32 v88, 0xc00, v56
	global_load_dwordx4 v[44:47], v[44:45], off
	v_ashrrev_i32_e32 v89, 31, v88
	v_lshl_add_u64 v[48:49], v[88:89], 4, s[70:71]
	v_add_u32_e32 v90, 0xd00, v56
	global_load_dwordx4 v[48:51], v[48:49], off
	v_ashrrev_i32_e32 v91, 31, v90
	v_lshl_add_u64 v[52:53], v[90:91], 4, s[70:71]
	v_add_u32_e32 v92, 0xe00, v56
	global_load_dwordx4 v[52:55], v[52:53], off
	v_ashrrev_i32_e32 v93, 31, v92
	v_lshl_add_u64 v[58:59], v[92:93], 4, s[70:71]
	v_add_u32_e32 v94, 0xf00, v56
	global_load_dwordx4 v[58:61], v[58:59], off
	v_ashrrev_i32_e32 v95, 31, v94
	s_waitcnt vmcnt(15)
	v_lshl_add_u64 v[62:63], v[94:95], 4, s[70:71]
	global_load_dwordx4 v[62:65], v[62:63], off
	v_lshlrev_b32_e32 v67, 14, v56
	v_and_b32_e32 v69, -4, v56
	v_and_b32_e32 v67, 0xc000, v67
	v_and_b32_e32 v66, -4, v66
	v_and_b32_e32 v68, -4, v68
	v_add_u32_e32 v69, v67, v69
	v_add_u32_e32 v66, v67, v66
	v_add_u32_e32 v68, v67, v68
	s_add_u32 s0, s88, 0x3e00000
	s_addc_u32 s1, s89, 0
	v_writelane_b32 v237, s0, 42
	s_waitcnt vmcnt(15)
	ds_write2st64_b32 v69, v0, v1 offset1:16
	ds_write2st64_b32 v69, v2, v3 offset0:32 offset1:48
	s_waitcnt vmcnt(14)
	ds_write2st64_b32 v66, v4, v5 offset1:16
	ds_write2st64_b32 v66, v6, v7 offset0:32 offset1:48
	s_waitcnt vmcnt(13)
	ds_write2st64_b32 v68, v8, v9 offset1:16
	ds_write2st64_b32 v68, v10, v11 offset0:32 offset1:48
	v_and_b32_e32 v0, -4, v70
	v_add_u32_e32 v0, v67, v0
	s_waitcnt vmcnt(12)
	ds_write2st64_b32 v0, v12, v13 offset1:16
	ds_write2st64_b32 v0, v14, v15 offset0:32 offset1:48
	v_and_b32_e32 v0, -4, v72
	v_add_u32_e32 v0, v67, v0
	s_waitcnt vmcnt(11)
	ds_write2st64_b32 v0, v16, v17 offset1:16
	ds_write2st64_b32 v0, v18, v19 offset0:32 offset1:48
	v_and_b32_e32 v0, -4, v74
	v_add_u32_e32 v0, v67, v0
	v_writelane_b32 v237, s1, 43
	s_waitcnt vmcnt(10)
	ds_write2st64_b32 v0, v20, v21 offset1:16
	ds_write2st64_b32 v0, v22, v23 offset0:32 offset1:48
	v_and_b32_e32 v0, -4, v76
	s_add_u32 s0, s88, 0x3d80000
	v_add_u32_e32 v0, v67, v0
	s_addc_u32 s1, s89, 0
	s_waitcnt vmcnt(9)
	ds_write2st64_b32 v0, v24, v25 offset1:16
	ds_write2st64_b32 v0, v26, v27 offset0:32 offset1:48
	v_and_b32_e32 v0, -4, v78
	v_writelane_b32 v237, s0, 44
	v_add_u32_e32 v0, v67, v0
	s_waitcnt vmcnt(8)
	ds_write2st64_b32 v0, v28, v29 offset1:16
	ds_write2st64_b32 v0, v30, v31 offset0:32 offset1:48
	v_writelane_b32 v237, s1, 45
	v_and_b32_e32 v0, -4, v80
	v_readlane_b32 s0, v237, 31
	v_add_u32_e32 v0, v67, v0
	s_cmpk_lt_i32 s0, 0x200
	s_waitcnt vmcnt(7)
	ds_write2st64_b32 v0, v32, v33 offset1:16
	ds_write2st64_b32 v0, v34, v35 offset0:32 offset1:48
	v_and_b32_e32 v0, -4, v82
	s_cselect_b64 s[2:3], -1, 0
	v_add_u32_e32 v0, v67, v0
	v_readlane_b32 s1, v237, 32
	v_writelane_b32 v237, s2, 46
	s_waitcnt vmcnt(6)
	ds_write2st64_b32 v0, v36, v37 offset1:16
	ds_write2st64_b32 v0, v38, v39 offset0:32 offset1:48
	v_and_b32_e32 v0, -4, v84
	v_writelane_b32 v237, s3, 47
	v_add_u32_e32 v0, v67, v0
	v_writelane_b32 v237, s80, 48
	s_waitcnt vmcnt(5)
	ds_write2st64_b32 v0, v40, v41 offset1:16
	ds_write2st64_b32 v0, v42, v43 offset0:32 offset1:48
	v_and_b32_e32 v0, -4, v86
	v_writelane_b32 v237, s81, 49
	v_add_u32_e32 v0, v67, v0
	v_writelane_b32 v237, s82, 50
	s_waitcnt vmcnt(4)
	ds_write2st64_b32 v0, v44, v45 offset1:16
	ds_write2st64_b32 v0, v46, v47 offset0:32 offset1:48
	v_and_b32_e32 v0, -4, v88
	v_writelane_b32 v237, s83, 51
	v_add_u32_e32 v0, v67, v0
	v_writelane_b32 v237, s84, 52
	s_waitcnt vmcnt(3)
	ds_write2st64_b32 v0, v48, v49 offset1:16
	ds_write2st64_b32 v0, v50, v51 offset0:32 offset1:48
	v_and_b32_e32 v0, -4, v90
	v_writelane_b32 v237, s85, 53
	v_add_u32_e32 v0, v67, v0
	v_writelane_b32 v237, s86, 54
	s_waitcnt vmcnt(2)
	ds_write2st64_b32 v0, v52, v53 offset1:16
	ds_write2st64_b32 v0, v54, v55 offset0:32 offset1:48
	v_and_b32_e32 v0, -4, v92
	v_writelane_b32 v237, s87, 55
	v_add_u32_e32 v0, v67, v0
	v_writelane_b32 v237, s88, 56
	s_waitcnt vmcnt(1)
	ds_write2st64_b32 v0, v58, v59 offset1:16
	ds_write2st64_b32 v0, v60, v61 offset0:32 offset1:48
	v_and_b32_e32 v0, -4, v94
	v_writelane_b32 v237, s89, 57
	v_add_u32_e32 v0, v67, v0
	s_cmpk_gt_i32 s0, 0x1ff
	v_writelane_b32 v237, s90, 58
	s_waitcnt vmcnt(0)
	ds_write2st64_b32 v0, v62, v63 offset1:16
	ds_write2st64_b32 v0, v64, v65 offset0:32 offset1:48
	s_waitcnt lgkmcnt(0)
	s_barrier
	v_writelane_b32 v237, s91, 59
	s_cbranch_scc1 .LBB0_594
	v_and_b32_e32 v5, 63, v56
	v_mov_b32_e32 v61, 0
	v_readlane_b32 s0, v237, 40
	v_lshlrev_b32_e32 v0, 3, v5
	v_mov_b32_e32 v1, v61
	v_readlane_b32 s1, v237, 41
	v_lshl_add_u64 v[2:3], v[56:57], 2, s[88:89]
	v_ashrrev_i32_e32 v4, 2, v56
	v_lshl_add_u64 v[64:65], s[0:1], 0, v[0:1]
	s_mov_b64 s[0:1], 0x3d00000
	v_lshl_add_u64 v[70:71], v[2:3], 0, s[0:1]
	v_lshlrev_b32_e32 v2, 6, v5
	v_mov_b32_e32 v3, v61
	v_lshl_add_u64 v[72:73], s[66:67], 0, v[2:3]
	s_mov_b64 s[0:1], 0x1000
	v_lshl_add_u64 v[74:75], v[72:73], 0, s[0:1]
	s_mov_b64 s[0:1], 0x2000
	v_lshl_add_u64 v[76:77], v[72:73], 0, s[0:1]
	s_mov_b64 s[0:1], 0x3000
	v_lshl_add_u64 v[78:79], v[72:73], 0, s[0:1]
	v_readlane_b32 s4, v237, 31
	s_lshl_b32 s0, s90, 6
	v_cmp_gt_i32_e64 s[6:7], 24, v56
	v_lshlrev_b32_e32 v6, 2, v56
	v_and_b32_e32 v58, -16, v4
	v_lshlrev_b32_e32 v60, 4, v5
	v_cmp_gt_i32_e64 s[8:9], 64, v56
	v_readlane_b32 s5, v237, 32
	s_lshl_b32 s12, s4, 6
	v_writelane_b32 v237, s0, 60
	v_mov_b32_e32 v2, 0x10000
	v_lshl_add_u64 v[0:1], s[88:89], 0, v[0:1]
	s_mov_b64 s[0:1], 0x4500400
	v_add_u32_e32 v99, 0x10100, v6
	v_ashrrev_i32_e32 v59, 31, v58
	v_lshl_add_u64 v[62:63], s[36:37], 0, v[60:61]
	v_lshl_add_u64 v[66:67], s[62:63], 0, v[60:61]
	v_lshl_add_u64 v[68:69], s[64:65], 0, v[60:61]
	v_lshrrev_b32_e32 v250, 6, v56
	v_lshlrev_b32_e32 v250, 10, v250
	v_mov_b32_e32 v251, 0
	v_lshl_add_u64 v[252:253], v[66:67], 0, v[250:251]
	global_load_dwordx4 v[186:189], v[252:253], off
	v_lshl_add_u64 v[252:253], v[68:69], 0, v[250:251]
	global_load_dwordx4 v[190:193], v[252:253], off
	v_lshlrev_b32_e32 v250, 4, v56
	v_add_u32_e32 v250, 0x10400, v250
	s_waitcnt vmcnt(0)
	ds_write_b128 v250, v[186:189]
	ds_write_b128 v250, v[190:193] offset:4096
	v_add_u32_e32 v234, 0x10400, v60
	s_waitcnt lgkmcnt(0)
	s_mov_b32 s3, 0
	v_cmp_eq_u32_e64 s[10:11], 0, v5
	v_add_u32_e32 v112, 0x10000, v6
	v_add_u32_e32 v113, 0x10200, v6
	v_add_u32_e32 v57, 0x10180, v6
	v_add_u32_e32 v114, s12, v4
	v_lshl_add_u32 v115, v4, 2, v2
	v_lshl_add_u64 v[80:81], v[0:1], 0, s[0:1]
	s_mov_b32 s22, 0x3fb504f3
	v_mov_b32_e32 v116, 0x3727c5ac
	v_mov_b32_e32 v117, 1
	v_mov_b32_e32 v118, 0xff61b1e6
	v_mov_b32_e32 v119, 0x10100
	v_mov_b32_e32 v120, 0x10180
	s_mov_b32 s2, s4
	v_writelane_b32 v237, s6, 62
	v_writelane_b32 v236, s8, 0
	s_nop 0
	v_writelane_b32 v237, s7, 63
	v_writelane_b32 v236, s9, 1
	s_branch .LBB0_548

.LBB0_548:
	s_barrier
	s_and_saveexec_b64 s[0:1], s[6:7]
	ds_write_b32 v99, v61
	s_or_b64 exec, exec, s[0:1]
	s_lshl_b32 s4, s2, 6
	s_ashr_i32 s5, s4, 31
	v_lshl_add_u64 v[82:83], s[4:5], 0, v[58:59]
	v_lshlrev_b64 v[0:1], 12, v[82:83]
	v_lshl_add_u64 v[0:1], v[62:63], 0, v[0:1]
	v_lshlrev_b64 v[2:3], 11, v[82:83]
	v_lshl_add_u64 v[2:3], v[64:65], 0, v[2:3]
	global_load_dwordx4 v[28:31], v[0:1], off
	global_load_dwordx4 v[20:23], v[0:1], off offset:1024
	global_load_dwordx4 v[24:27], v[0:1], off offset:2048
	global_load_dwordx4 v[16:19], v[0:1], off offset:3072
	global_load_dwordx2 v[84:85], v[2:3], off
	global_load_dwordx2 v[88:89], v[2:3], off offset:512
	global_load_dwordx2 v[90:91], v[2:3], off offset:1024
	global_load_dwordx2 v[92:93], v[2:3], off offset:1536
	global_load_dwordx4 v[182:185], v[72:73], off
	global_load_dwordx4 v[186:189], v[72:73], off offset:16
	global_load_dwordx4 v[190:193], v[72:73], off offset:32
	global_load_dwordx4 v[194:197], v[72:73], off offset:48
	global_load_dwordx4 v[198:201], v[74:75], off
	global_load_dwordx4 v[202:205], v[74:75], off offset:16
	global_load_dwordx4 v[206:209], v[74:75], off offset:32
	global_load_dwordx4 v[210:213], v[74:75], off offset:48
	global_load_dwordx4 v[214:217], v[76:77], off
	global_load_dwordx4 v[218:221], v[76:77], off offset:16
	global_load_dwordx4 v[222:225], v[76:77], off offset:32
	global_load_dwordx4 v[226:229], v[76:77], off offset:48
	global_load_dwordx4 v[230:233], v[78:79], off
	global_load_dwordx4 v[238:241], v[78:79], off offset:16
	global_load_dwordx4 v[242:245], v[78:79], off offset:32
	global_load_dwordx4 v[246:249], v[78:79], off offset:48
	global_load_dword v162, v61, s[72:73] offset:0
	global_load_dword v163, v61, s[72:73] offset:4
	global_load_dword v164, v61, s[72:73] offset:8
	global_load_dword v165, v61, s[72:73] offset:12
	global_load_dword v166, v61, s[72:73] offset:16
	global_load_dword v167, v61, s[72:73] offset:20
	global_load_dword v168, v61, s[72:73] offset:24
	global_load_dword v169, v61, s[72:73] offset:28
	global_load_dword v170, v61, s[72:73] offset:32
	global_load_dword v171, v61, s[72:73] offset:36
	global_load_dword v172, v61, s[72:73] offset:40
	global_load_dword v173, v61, s[72:73] offset:44
	global_load_dword v174, v61, s[72:73] offset:48
	global_load_dword v175, v61, s[72:73] offset:52
	global_load_dword v176, v61, s[72:73] offset:56
	global_load_dword v177, v61, s[72:73] offset:60
	global_load_dwordx4 v[178:181], v61, s[68:69] offset:0
	v_writelane_b32 v236, s2, 2
	s_mov_b32 s0, s4
	s_ashr_i32 s13, s12, 31
	v_writelane_b32 v236, s0, 4
	v_lshl_add_u64 v[0:1], v[58:59], 0, s[12:13]
	v_lshlrev_b64 v[0:1], 11, v[0:1]
	v_writelane_b32 v236, s1, 5
	s_mov_b32 s0, s12
	v_writelane_b32 v236, s0, 6
	v_lshl_add_u64 v[86:87], v[80:81], 0, v[0:1]
	s_mov_b32 s7, 0
	v_mov_b32_e32 v121, v115
	v_writelane_b32 v236, s1, 7
	s_branch .LBB0_552

.LBB0_552:
	s_add_i32 s23, s7, 1
	s_waitcnt vmcnt(0)
	v_mov_b64_e32 v[38:39], v[84:85]
	v_mov_b64_e32 v[32:33], v[92:93]
	v_mov_b64_e32 v[34:35], v[90:91]
	v_mov_b64_e32 v[36:37], v[88:89]
	v_mov_b32_e32 v0, s23
	v_min_u32_e32 v0, 15, v0
	v_mov_b32_e32 v1, 0
	v_lshl_add_u64 v[0:1], v[82:83], 0, v[0:1]
	v_lshlrev_b64 v[2:3], 12, v[0:1]
	v_lshlrev_b64 v[0:1], 11, v[0:1]
	v_lshl_add_u64 v[12:13], v[62:63], 0, v[2:3]
	v_lshl_add_u64 v[92:93], v[64:65], 0, v[0:1]
	global_load_dwordx4 v[0:3], v[12:13], off
	global_load_dwordx2 v[84:85], v[92:93], off
	global_load_dwordx4 v[4:7], v[12:13], off offset:1024
	global_load_dwordx2 v[88:89], v[92:93], off offset:512
	global_load_dwordx4 v[8:11], v[12:13], off offset:2048
	global_load_dwordx2 v[90:91], v[92:93], off offset:1024
	s_nop 0
	global_load_dwordx4 v[12:15], v[12:13], off offset:3072
	s_nop 0
	global_load_dwordx2 v[92:93], v[92:93], off offset:1536
	v_lshlrev_b32_e32 v40, 16, v38
	v_and_b32_e32 v41, 0xffff0000, v38
	v_lshlrev_b32_e32 v38, 16, v39
	v_and_b32_e32 v39, 0xffff0000, v39
	v_lshlrev_b32_e32 v54, 16, v36
	v_and_b32_e32 v55, 0xffff0000, v36
	v_lshlrev_b32_e32 v94, 16, v37
	v_and_b32_e32 v95, 0xffff0000, v37
	v_lshlrev_b32_e32 v96, 16, v34
	v_and_b32_e32 v97, 0xffff0000, v34
	v_lshlrev_b32_e32 v100, 16, v35
	v_and_b32_e32 v101, 0xffff0000, v35
	v_lshlrev_b32_e32 v102, 16, v32
	v_and_b32_e32 v103, 0xffff0000, v32
	v_lshlrev_b32_e32 v104, 16, v33
	v_and_b32_e32 v105, 0xffff0000, v33
	v_pk_fma_f32 v[106:107], v[30:31], s[22:23], v[38:39] op_sel_hi:[1,0,1]
	ds_read_b128 v[30:33], v234
	ds_read_b128 v[34:37], v234 offset:4096
	v_pk_fma_f32 v[28:29], v[28:29], s[22:23], v[40:41] op_sel_hi:[1,0,1]
	v_pk_fma_f32 v[20:21], v[20:21], s[22:23], v[54:55] op_sel_hi:[1,0,1]
	v_add_f32_e32 v38, v28, v29
	v_add_f32_e32 v38, v38, v106
	v_pk_fma_f32 v[22:23], v[22:23], s[22:23], v[94:95] op_sel_hi:[1,0,1]
	v_add_f32_e32 v54, v20, v21
	v_pk_fma_f32 v[24:25], v[24:25], s[22:23], v[96:97] op_sel_hi:[1,0,1]
	v_add_f32_e32 v38, v107, v38
	v_add_f32_e32 v54, v54, v22
	v_pk_fma_f32 v[26:27], v[26:27], s[22:23], v[100:101] op_sel_hi:[1,0,1]
	v_add_f32_e32 v55, v24, v25
	v_add_f32_e32 v98, 0, v38
	v_add_f32_e32 v54, v23, v54
	v_add_f32_e32 v55, v55, v26
	v_add_f32_e32 v54, v98, v54
	v_add_f32_e32 v55, v27, v55
	v_pk_fma_f32 v[16:17], v[16:17], s[22:23], v[102:103] op_sel_hi:[1,0,1]
	v_add_f32_e32 v54, v54, v55
	v_pk_fma_f32 v[18:19], v[18:19], s[22:23], v[104:105] op_sel_hi:[1,0,1]
	v_add_f32_e32 v55, v16, v17
	v_add_f32_e32 v55, v55, v18
	v_add_f32_e32 v55, v19, v55
	v_add_f32_e32 v54, v54, v55
	ds_read_b128 v[38:41], v60
	ds_read_b128 v[42:45], v60 offset:4096
	ds_read_b128 v[46:49], v60 offset:8192
	ds_read_b128 v[50:53], v60 offset:12288
	ds_read_b128 v[108:111], v60 offset:16384
	ds_read_b128 v[122:125], v60 offset:20480
	ds_read_b128 v[130:133], v60 offset:24576
	ds_read_b128 v[134:137], v60 offset:28672
	ds_read_b128 v[138:141], v60 offset:32768
	ds_read_b128 v[142:145], v60 offset:36864
	ds_read_b128 v[146:149], v60 offset:40960
	ds_read_b128 v[150:153], v60 offset:45056
	ds_read_b128 v[154:157], v60 offset:49152
	v_add_f32_dpp v54, v54, v54 quad_perm:[1,0,3,2] row_mask:0xf bank_mask:0xf bound_ctrl:1
	s_nop 1
	v_add_f32_dpp v54, v54, v54 quad_perm:[2,3,0,1] row_mask:0xf bank_mask:0xf bound_ctrl:1
	s_nop 1
	v_add_f32_dpp v54, v54, v54 row_half_mirror row_mask:0xf bank_mask:0xf bound_ctrl:1
	s_nop 1
	v_add_f32_dpp v54, v54, v54 row_mirror row_mask:0xf bank_mask:0xf bound_ctrl:1
	s_nop 0
	v_readlane_b32 s2, v54, 16
	v_readlane_b32 s4, v54, 48
	v_readlane_b32 s0, v54, 0
	v_readlane_b32 s1, v54, 32
	v_mov_b32_e32 v54, s2
	v_mov_b32_e32 v55, s4
	v_pk_add_f32 v[54:55], s[0:1], v[54:55]
	s_nop 0
	v_add_f32_e32 v54, v54, v55
	v_mul_f32_e32 v54, 0x3a800000, v54
	v_pk_add_f32 v[28:29], v[28:29], v[54:55] op_sel_hi:[1,0] neg_lo:[0,1] neg_hi:[0,1]
	v_pk_add_f32 v[126:127], v[106:107], v[54:55] op_sel_hi:[1,0] neg_lo:[0,1] neg_hi:[0,1]
	v_pk_mul_f32 v[104:105], v[28:29], v[28:29]
	v_pk_mul_f32 v[106:107], v[126:127], v[126:127]
	v_pk_add_f32 v[158:159], v[20:21], v[54:55] op_sel_hi:[1,0] neg_lo:[0,1] neg_hi:[0,1]
	v_pk_add_f32 v[160:161], v[22:23], v[54:55] op_sel_hi:[1,0] neg_lo:[0,1] neg_hi:[0,1]
	v_pk_add_f32 v[100:101], v[24:25], v[54:55] op_sel_hi:[1,0] neg_lo:[0,1] neg_hi:[0,1]
	v_pk_add_f32 v[102:103], v[26:27], v[54:55] op_sel_hi:[1,0] neg_lo:[0,1] neg_hi:[0,1]
	v_pk_add_f32 v[94:95], v[16:17], v[54:55] op_sel_hi:[1,0] neg_lo:[0,1] neg_hi:[0,1]
	v_pk_add_f32 v[96:97], v[18:19], v[54:55] op_sel_hi:[1,0] neg_lo:[0,1] neg_hi:[0,1]
	v_add_f32_e32 v54, v104, v105
	v_add_f32_e32 v54, v106, v54
	v_pk_mul_f32 v[20:21], v[158:159], v[158:159]
	v_add_f32_e32 v54, v107, v54
	v_add_f32_e32 v20, v20, v54
	v_pk_mul_f32 v[22:23], v[160:161], v[160:161]
	v_add_f32_e32 v20, v21, v20
	v_add_f32_e32 v20, v22, v20
	v_pk_mul_f32 v[24:25], v[100:101], v[100:101]
	v_add_f32_e32 v20, v23, v20
	v_add_f32_e32 v20, v24, v20
	v_pk_mul_f32 v[26:27], v[102:103], v[102:103]
	v_add_f32_e32 v20, v25, v20
	v_add_f32_e32 v20, v26, v20
	v_pk_mul_f32 v[16:17], v[94:95], v[94:95]
	v_add_f32_e32 v20, v27, v20
	v_add_f32_e32 v16, v16, v20
	v_pk_mul_f32 v[18:19], v[96:97], v[96:97]
	v_add_f32_e32 v16, v17, v16
	v_add_f32_e32 v16, v18, v16
	v_add_f32_e32 v16, v19, v16
	s_nop 1
	v_add_f32_dpp v16, v16, v16 quad_perm:[1,0,3,2] row_mask:0xf bank_mask:0xf bound_ctrl:1
	s_nop 1
	v_add_f32_dpp v16, v16, v16 quad_perm:[2,3,0,1] row_mask:0xf bank_mask:0xf bound_ctrl:1
	s_nop 1
	v_add_f32_dpp v16, v16, v16 row_half_mirror row_mask:0xf bank_mask:0xf bound_ctrl:1
	s_nop 1
	v_add_f32_dpp v16, v16, v16 row_mirror row_mask:0xf bank_mask:0xf bound_ctrl:1
	s_nop 0
	v_readlane_b32 s2, v16, 16
	v_readlane_b32 s4, v16, 48
	v_readlane_b32 s0, v16, 0
	v_readlane_b32 s1, v16, 32
	v_mov_b32_e32 v16, s2
	v_mov_b32_e32 v17, s4
	v_pk_add_f32 v[16:17], s[0:1], v[16:17]
	s_mov_b32 s0, 0x800000
	v_add_f32_e32 v16, v16, v17
	v_fmamk_f32 v16, v16, 0x3a800000, v116
	v_cmp_gt_f32_e32 vcc, s0, v16
	v_mul_f32_e32 v17, 0x4b800000, v16
	s_nop 0
	v_cndmask_b32_e32 v16, v16, v17, vcc
	v_rsq_f32_e32 v54, v16
	ds_read_b128 v[16:19], v60 offset:53248
	s_waitcnt lgkmcnt(15)
	ds_read_b128 v[20:23], v60 offset:57344
	s_waitcnt lgkmcnt(15)
	ds_read_b128 v[24:27], v60 offset:61440
	s_waitcnt lgkmcnt(15)
	v_mul_f32_e32 v55, 0x45800000, v54
	v_cndmask_b32_e32 v98, v54, v55, vcc
	v_pk_mul_f32 v[28:29], v[28:29], v[98:99] op_sel_hi:[1,0]
	v_pk_fma_f32 v[106:107], v[30:31], v[28:29], v[34:35]
	v_pk_mul_f32 v[28:29], v[126:127], v[98:99] op_sel_hi:[1,0]
	s_waitcnt lgkmcnt(2)
	v_mul_f32_e32 v17, v107, v17
	v_pk_fma_f32 v[104:105], v[32:33], v[28:29], v[36:37]
	v_cvt_pk_bf16_f32 v28, v106, v107
	v_cvt_pk_bf16_f32 v29, v104, v105
	global_store_dwordx2 v[86:87], v[28:29], off offset:-1024
	v_mul_f32_e32 v28, v39, v107
	v_fmac_f32_e32 v28, v38, v106
	ds_read_b128 v[32:35], v234 offset:1024
	ds_read_b128 v[36:39], v234 offset:5120
	v_fmac_f32_e32 v28, v104, v40
	v_fmac_f32_e32 v28, v105, v41
	v_add_f32_e32 v54, 0, v28
	v_mul_f32_e32 v28, v107, v43
	v_fmac_f32_e32 v28, v106, v42
	v_fmac_f32_e32 v28, v104, v44
	v_fmac_f32_e32 v28, v105, v45
	v_add_f32_e32 v55, 0, v28
	v_mul_f32_e32 v28, v107, v47
	v_fmac_f32_e32 v28, v106, v46
	v_fmac_f32_e32 v28, v104, v48
	v_fmac_f32_e32 v28, v105, v49
	v_add_f32_e32 v46, 0, v28
	v_mul_f32_e32 v28, v107, v51
	v_fmac_f32_e32 v28, v106, v50
	v_fmac_f32_e32 v28, v104, v52
	v_fmac_f32_e32 v28, v105, v53
	v_add_f32_e32 v45, 0, v28
	v_mul_f32_e32 v28, v107, v109
	v_fmac_f32_e32 v28, v106, v108
	v_fmac_f32_e32 v28, v104, v110
	v_fmac_f32_e32 v28, v105, v111
	v_add_f32_e32 v44, 0, v28
	v_mul_f32_e32 v28, v107, v123
	v_fmac_f32_e32 v28, v106, v122
	v_fmac_f32_e32 v28, v104, v124
	v_fmac_f32_e32 v28, v105, v125
	v_add_f32_e32 v53, 0, v28
	v_mul_f32_e32 v28, v107, v131
	v_fmac_f32_e32 v28, v106, v130
	v_fmac_f32_e32 v28, v104, v132
	v_fmac_f32_e32 v28, v105, v133
	v_add_f32_e32 v52, 0, v28
	v_mul_f32_e32 v28, v107, v135
	v_fmac_f32_e32 v28, v106, v134
	v_fmac_f32_e32 v28, v104, v136
	v_fmac_f32_e32 v28, v105, v137
	v_add_f32_e32 v51, 0, v28
	v_mul_f32_e32 v28, v107, v139
	v_fmac_f32_e32 v28, v106, v138
	v_fmac_f32_e32 v28, v104, v140
	v_fmac_f32_e32 v28, v105, v141
	v_add_f32_e32 v50, 0, v28
	v_mul_f32_e32 v28, v107, v143
	v_fmac_f32_e32 v28, v106, v142
	v_fmac_f32_e32 v28, v104, v144
	v_fmac_f32_e32 v28, v105, v145
	v_add_f32_e32 v49, 0, v28
	v_mul_f32_e32 v28, v107, v147
	v_fmac_f32_e32 v28, v106, v146
	v_fmac_f32_e32 v28, v104, v148
	v_fmac_f32_e32 v28, v105, v149
	v_add_f32_e32 v48, 0, v28
	v_mul_f32_e32 v28, v107, v151
	v_fmac_f32_e32 v17, v106, v16
	s_waitcnt lgkmcnt(3)
	v_mul_f32_e32 v16, v107, v21
	v_fmac_f32_e32 v28, v106, v150
	v_fmac_f32_e32 v16, v106, v20
	v_fmac_f32_e32 v28, v104, v152
	v_fmac_f32_e32 v16, v104, v22
	v_fmac_f32_e32 v28, v105, v153
	v_fmac_f32_e32 v16, v105, v23
	v_add_f32_e32 v131, 0, v28
	v_mul_f32_e32 v28, v107, v155
	v_add_f32_e32 v122, 0, v16
	s_waitcnt lgkmcnt(2)
	v_mul_f32_e32 v16, v107, v25
	v_fmac_f32_e32 v28, v106, v154
	v_fmac_f32_e32 v16, v106, v24
	v_fmac_f32_e32 v28, v104, v156
	v_fmac_f32_e32 v17, v104, v18
	v_fmac_f32_e32 v16, v104, v26
	v_fmac_f32_e32 v28, v105, v157
	v_fmac_f32_e32 v17, v105, v19
	v_fmac_f32_e32 v16, v105, v27
	v_pk_mul_f32 v[40:41], v[158:159], v[98:99] op_sel_hi:[1,0]
	v_add_f32_e32 v125, 0, v28
	v_add_f32_e32 v124, 0, v17
	v_add_f32_e32 v123, 0, v16
	s_waitcnt lgkmcnt(0)
	v_pk_fma_f32 v[108:109], v[40:41], v[32:33], v[36:37]
	ds_read_b128 v[40:43], v60 offset:1024
	ds_read_b128 v[134:137], v60 offset:21504
	v_pk_mul_f32 v[32:33], v[160:161], v[98:99] op_sel_hi:[1,0]
	ds_read_b128 v[142:145], v60 offset:29696
	v_pk_fma_f32 v[110:111], v[32:33], v[34:35], v[38:39]
	s_waitcnt lgkmcnt(2)
	v_mul_f32_e32 v36, v109, v41
	v_cvt_pk_bf16_f32 v32, v108, v109
	v_cvt_pk_bf16_f32 v33, v110, v111
	v_fmac_f32_e32 v36, v108, v40
	global_store_dwordx2 v[86:87], v[32:33], off offset:-512
	ds_read_b128 v[32:35], v60 offset:5120
	v_fmac_f32_e32 v36, v110, v42
	v_fmac_f32_e32 v36, v111, v43
	v_add_f32_e32 v126, v54, v36
	s_waitcnt lgkmcnt(2)
	v_mul_f32_e32 v54, v109, v135
	s_waitcnt lgkmcnt(1)
	v_mul_f32_e32 v135, v109, v143
	v_fmac_f32_e32 v135, v108, v142
	v_fmac_f32_e32 v135, v110, v144
	v_fmac_f32_e32 v135, v111, v145
	ds_read_b128 v[144:147], v60 offset:50176
	s_waitcnt lgkmcnt(1)
	v_mul_f32_e32 v33, v109, v33
	v_fmac_f32_e32 v33, v108, v32
	v_fmac_f32_e32 v33, v110, v34
	v_fmac_f32_e32 v33, v111, v35
	ds_read_b128 v[36:39], v60 offset:9216
	v_add_f32_e32 v127, v55, v33
	ds_read_b128 v[32:35], v60 offset:13312
	ds_read_b128 v[40:43], v60 offset:17408
	ds_read_b128 v[138:141], v60 offset:25600
	v_fmac_f32_e32 v54, v108, v134
	v_fmac_f32_e32 v54, v110, v136
	s_waitcnt lgkmcnt(3)
	v_mul_f32_e32 v37, v109, v37
	s_waitcnt lgkmcnt(2)
	v_mul_f32_e32 v33, v109, v33
	v_fmac_f32_e32 v54, v111, v137
	v_fmac_f32_e32 v37, v108, v36
	v_fmac_f32_e32 v33, v108, v32
	v_add_f32_e32 v133, v53, v54
	s_waitcnt lgkmcnt(0)
	v_mul_f32_e32 v53, v109, v139
	v_fmac_f32_e32 v37, v110, v38
	v_fmac_f32_e32 v33, v110, v34
	v_mul_f32_e32 v41, v109, v41
	v_fmac_f32_e32 v53, v108, v138
	v_fmac_f32_e32 v37, v111, v39
	v_fmac_f32_e32 v33, v111, v35
	v_fmac_f32_e32 v41, v108, v40
	v_fmac_f32_e32 v53, v110, v140
	v_add_f32_e32 v129, v46, v37
	v_add_f32_e32 v130, v45, v33
	v_fmac_f32_e32 v41, v110, v42
	v_fmac_f32_e32 v53, v111, v141
	v_fmac_f32_e32 v41, v111, v43
	v_add_f32_e32 v134, v52, v53
	ds_read_b128 v[52:55], v60 offset:33792
	ds_read_b128 v[138:141], v60 offset:37888
	v_add_f32_e32 v132, v44, v41
	v_add_f32_e32 v135, v51, v135
	s_waitcnt lgkmcnt(1)
	v_mul_f32_e32 v51, v109, v53
	v_fmac_f32_e32 v51, v108, v52
	v_fmac_f32_e32 v51, v110, v54
	v_fmac_f32_e32 v51, v111, v55
	v_add_f32_e32 v136, v50, v51
	ds_read_b128 v[50:53], v60 offset:41984
	s_waitcnt lgkmcnt(1)
	v_mul_f32_e32 v54, v109, v139
	v_fmac_f32_e32 v54, v108, v138
	v_fmac_f32_e32 v54, v110, v140
	v_fmac_f32_e32 v54, v111, v141
	v_add_f32_e32 v137, v49, v54
	ds_read_b128 v[140:143], v60 offset:46080
	s_waitcnt lgkmcnt(1)
	v_mul_f32_e32 v49, v109, v51
	v_fmac_f32_e32 v49, v108, v50
	v_fmac_f32_e32 v49, v110, v52
	v_fmac_f32_e32 v49, v111, v53
	v_add_f32_e32 v138, v48, v49
	ds_read_b128 v[48:51], v234 offset:2048
	ds_read_b128 v[52:55], v234 offset:6144
	s_waitcnt lgkmcnt(2)
	v_mul_f32_e32 v139, v109, v141
	v_fmac_f32_e32 v139, v108, v140
	v_fmac_f32_e32 v139, v110, v142
	v_fmac_f32_e32 v139, v111, v143
	ds_read_b128 v[140:143], v60 offset:54272
	v_add_f32_e32 v131, v131, v139
	v_mul_f32_e32 v139, v109, v145
	v_fmac_f32_e32 v139, v108, v144
	v_fmac_f32_e32 v139, v110, v146
	v_fmac_f32_e32 v139, v111, v147
	ds_read_b128 v[144:147], v60 offset:58368
	v_add_f32_e32 v139, v125, v139
	s_waitcnt lgkmcnt(1)
	v_mul_f32_e32 v125, v109, v141
	v_fmac_f32_e32 v125, v108, v140
	v_fmac_f32_e32 v125, v110, v142
	v_fmac_f32_e32 v125, v111, v143
	ds_read_b128 v[140:143], v60 offset:62464
	v_add_f32_e32 v148, v124, v125
	s_waitcnt lgkmcnt(1)
	v_mul_f32_e32 v124, v109, v145
	v_fmac_f32_e32 v124, v108, v144
	v_fmac_f32_e32 v124, v110, v146
	v_fmac_f32_e32 v124, v111, v147
	v_add_f32_e32 v144, v122, v124
	s_waitcnt lgkmcnt(0)
	v_mul_f32_e32 v122, v109, v141
	v_fmac_f32_e32 v122, v108, v140
	v_fmac_f32_e32 v122, v110, v142
	v_fmac_f32_e32 v122, v111, v143
	v_add_f32_e32 v142, v123, v122
	v_mov_b32_e32 v122, v106
	v_mov_b32_e32 v123, v108
	v_mov_b32_e32 v108, v107
	v_mov_b32_e32 v106, v186
	v_mov_b32_e32 v124, v182
	v_mov_b32_e32 v140, v190
	v_mov_b32_e32 v125, v198
	v_mov_b32_e32 v107, v202
	v_pk_mul_f32 v[106:107], v[108:109], v[106:107]
	v_mov_b32_e32 v36, v187
	v_pk_fma_f32 v[106:107], v[122:123], v[124:125], v[106:107]
	v_mov_b32_e32 v124, v104
	v_mov_b32_e32 v125, v110
	v_mov_b32_e32 v110, v105
	v_mov_b32_e32 v104, v194
	v_mov_b32_e32 v141, v206
	v_pk_fma_f32 v[106:107], v[124:125], v[140:141], v[106:107]
	v_mov_b32_e32 v105, v210
	v_mov_b32_e32 v32, v183
	v_mov_b32_e32 v37, v203
	v_pk_mul_f32 v[24:25], v[108:109], v[36:37]
	v_pk_fma_f32 v[104:105], v[110:111], v[104:105], v[106:107]
	v_mov_b32_e32 v33, v199
	v_pk_fma_f32 v[24:25], v[122:123], v[32:33], v[24:25]
	v_mov_b32_e32 v40, v191
	v_add_f32_e32 v16, 0, v104
	v_mov_b32_e32 v41, v207
	v_pk_fma_f32 v[20:21], v[124:125], v[40:41], v[24:25]
	v_mov_b32_e32 v44, v195
	v_add_f32_e32 v107, v16, v105
	v_mov_b32_e32 v45, v211
	v_pk_fma_f32 v[16:17], v[110:111], v[44:45], v[20:21]
	v_mov_b32_e32 v20, v188
	v_add_f32_e32 v16, 0, v16
	v_mov_b32_e32 v21, v204
	v_add_f32_e32 v105, v16, v17
	v_mov_b32_e32 v16, v184
	v_mov_b32_e32 v17, v200
	v_pk_mul_f32 v[20:21], v[108:109], v[20:21]
	v_mov_b32_e32 v38, v189
	v_pk_fma_f32 v[16:17], v[122:123], v[16:17], v[20:21]
	v_mov_b32_e32 v20, v192
	v_mov_b32_e32 v21, v208
	v_pk_fma_f32 v[16:17], v[124:125], v[20:21], v[16:17]
	v_mov_b32_e32 v20, v196
	v_mov_b32_e32 v21, v212
	v_pk_fma_f32 v[16:17], v[110:111], v[20:21], v[16:17]
	v_mov_b32_e32 v34, v185
	v_add_f32_e32 v16, 0, v16
	v_add_f32_e32 v106, v16, v17
	v_mov_b32_e32 v39, v205
	v_pk_mul_f32 v[16:17], v[108:109], v[38:39]
	v_mov_b32_e32 v42, v193
	v_mov_b32_e32 v35, v201
	v_pk_fma_f32 v[16:17], v[122:123], v[34:35], v[16:17]
	v_mov_b32_e32 v46, v197
	v_mov_b32_e32 v43, v209
	v_pk_fma_f32 v[16:17], v[124:125], v[42:43], v[16:17]
	v_pk_mul_f32 v[20:21], v[102:103], v[98:99] op_sel_hi:[1,0]
	v_mov_b32_e32 v47, v213
	v_pk_fma_f32 v[16:17], v[110:111], v[46:47], v[16:17]
	v_pk_fma_f32 v[50:51], v[20:21], v[50:51], v[54:55]
	v_add_f32_e32 v16, 0, v16
	v_add_f32_e32 v104, v16, v17
	v_pk_mul_f32 v[16:17], v[100:101], v[98:99] op_sel_hi:[1,0]
	v_cvt_pk_bf16_f32 v21, v50, v51
	v_pk_fma_f32 v[48:49], v[16:17], v[48:49], v[52:53]
	ds_read_b128 v[16:19], v60 offset:2048
	v_cvt_pk_bf16_f32 v20, v48, v49
	global_store_dwordx2 v[86:87], v[20:21], off
	ds_read_b128 v[20:23], v60 offset:6144
	v_pk_mul_f32 v[46:47], v[94:95], v[98:99] op_sel_hi:[1,0]
	s_waitcnt lgkmcnt(1)
	v_mul_f32_e32 v17, v49, v17
	v_fmac_f32_e32 v17, v48, v16
	v_fmac_f32_e32 v17, v50, v18
	v_fmac_f32_e32 v17, v51, v19
	v_add_f32_e32 v42, v126, v17
	ds_read_b128 v[16:19], v60 offset:10240
	s_waitcnt lgkmcnt(1)
	v_mul_f32_e32 v21, v49, v21
	v_fmac_f32_e32 v21, v48, v20
	v_fmac_f32_e32 v21, v50, v22
	v_fmac_f32_e32 v21, v51, v23
	v_add_f32_e32 v41, v127, v21
	ds_read_b128 v[20:23], v60 offset:14336
	s_waitcnt lgkmcnt(1)
	v_mul_f32_e32 v17, v49, v17
	v_fmac_f32_e32 v17, v48, v16
	v_fmac_f32_e32 v17, v50, v18
	v_fmac_f32_e32 v17, v51, v19
	v_add_f32_e32 v40, v129, v17
	ds_read_b128 v[16:19], v60 offset:18432
	ds_read_b128 v[32:35], v234 offset:3072
	ds_read_b128 v[36:39], v234 offset:7168
	s_waitcnt lgkmcnt(3)
	v_mul_f32_e32 v21, v49, v21
	v_fmac_f32_e32 v21, v48, v20
	v_fmac_f32_e32 v21, v50, v22
	v_fmac_f32_e32 v21, v51, v23
	v_add_f32_e32 v45, v130, v21
	ds_read_b128 v[20:23], v60 offset:22528
	s_waitcnt lgkmcnt(3)
	v_mul_f32_e32 v17, v49, v17
	v_fmac_f32_e32 v17, v48, v16
	v_fmac_f32_e32 v17, v50, v18
	v_fmac_f32_e32 v17, v51, v19
	v_add_f32_e32 v44, v132, v17
	ds_read_b128 v[16:19], v60 offset:26624
	s_waitcnt lgkmcnt(1)
	v_mul_f32_e32 v21, v49, v21
	v_fmac_f32_e32 v21, v48, v20
	v_fmac_f32_e32 v21, v50, v22
	v_fmac_f32_e32 v21, v51, v23
	v_add_f32_e32 v124, v133, v21
	ds_read_b128 v[20:23], v60 offset:30720
	s_waitcnt lgkmcnt(1)
	v_mul_f32_e32 v17, v49, v17
	v_fmac_f32_e32 v17, v48, v16
	v_fmac_f32_e32 v17, v50, v18
	v_fmac_f32_e32 v17, v51, v19
	s_waitcnt lgkmcnt(0)
	v_mul_f32_e32 v21, v49, v21
	v_fmac_f32_e32 v21, v48, v20
	v_fmac_f32_e32 v21, v50, v22
	v_add_f32_e32 v123, v134, v17
	ds_read_b128 v[16:19], v60 offset:34816
	v_fmac_f32_e32 v21, v51, v23
	v_add_f32_e32 v122, v135, v21
	ds_read_b128 v[20:23], v60 offset:38912
	s_waitcnt lgkmcnt(1)
	v_mul_f32_e32 v17, v49, v17
	v_fmac_f32_e32 v17, v48, v16
	v_fmac_f32_e32 v17, v50, v18
	s_waitcnt lgkmcnt(0)
	v_mul_f32_e32 v21, v49, v21
	v_fmac_f32_e32 v21, v48, v20
	v_fmac_f32_e32 v17, v51, v19
	v_fmac_f32_e32 v21, v50, v22
	v_add_f32_e32 v111, v136, v17
	ds_read_b128 v[16:19], v60 offset:43008
	v_fmac_f32_e32 v21, v51, v23
	v_add_f32_e32 v110, v137, v21
	ds_read_b128 v[20:23], v60 offset:47104
	s_waitcnt lgkmcnt(1)
	v_mul_f32_e32 v17, v49, v17
	v_fmac_f32_e32 v17, v48, v16
	v_fmac_f32_e32 v17, v50, v18
	s_waitcnt lgkmcnt(0)
	v_mul_f32_e32 v21, v49, v21
	v_fmac_f32_e32 v21, v48, v20
	v_fmac_f32_e32 v17, v51, v19
	v_fmac_f32_e32 v21, v50, v22
	v_add_f32_e32 v109, v138, v17
	ds_read_b128 v[16:19], v60 offset:51200
	v_fmac_f32_e32 v21, v51, v23
	v_add_f32_e32 v108, v131, v21
	ds_read_b128 v[20:23], v60 offset:55296
	s_waitcnt lgkmcnt(1)
	v_mul_f32_e32 v17, v49, v17
	v_fmac_f32_e32 v17, v48, v16
	v_fmac_f32_e32 v17, v50, v18
	s_waitcnt lgkmcnt(0)
	v_mul_f32_e32 v21, v49, v21
	v_fmac_f32_e32 v21, v48, v20
	v_fmac_f32_e32 v17, v51, v19
	v_fmac_f32_e32 v21, v50, v22
	v_add_f32_e32 v103, v139, v17
	ds_read_b128 v[16:19], v60 offset:59392
	v_fmac_f32_e32 v21, v51, v23
	v_add_f32_e32 v102, v148, v21
	ds_read_b128 v[20:23], v60 offset:63488
	s_waitcnt lgkmcnt(1)
	v_mul_f32_e32 v17, v49, v17
	v_fmac_f32_e32 v17, v48, v16
	v_fmac_f32_e32 v17, v50, v18
	s_waitcnt lgkmcnt(0)
	v_mul_f32_e32 v16, v49, v21
	v_fmac_f32_e32 v16, v48, v20
	v_fmac_f32_e32 v16, v50, v22
	v_fmac_f32_e32 v17, v51, v19
	v_fmac_f32_e32 v16, v51, v23
	v_add_f32_e32 v100, v144, v17
	v_add_f32_e32 v101, v142, v16
	v_pk_fma_f32 v[52:53], v[46:47], v[32:33], v[36:37]
	v_pk_mul_f32 v[32:33], v[96:97], v[98:99] op_sel_hi:[1,0]
	ds_read_b128 v[94:97], v60 offset:3072
	v_pk_fma_f32 v[54:55], v[32:33], v[34:35], v[38:39]
	v_cvt_pk_bf16_f32 v32, v52, v53
	v_cvt_pk_bf16_f32 v33, v54, v55
	global_store_dwordx2 v[86:87], v[32:33], off offset:512
	ds_read_b128 v[32:35], v60 offset:7168
	s_waitcnt lgkmcnt(1)
	v_mul_f32_e32 v36, v53, v95
	v_fmac_f32_e32 v36, v52, v94
	v_fmac_f32_e32 v36, v54, v96
	v_fmac_f32_e32 v36, v55, v97
	v_add_f32_e32 v94, v42, v36
	ds_read_b128 v[36:39], v60 offset:11264
	ds_read_b128 v[130:133], v60 offset:15360
	s_waitcnt lgkmcnt(2)
	v_mul_f32_e32 v33, v53, v33
	v_fmac_f32_e32 v33, v52, v32
	v_fmac_f32_e32 v33, v54, v34
	s_waitcnt lgkmcnt(1)
	v_mul_f32_e32 v32, v53, v37
	v_fmac_f32_e32 v32, v52, v36
	v_fmac_f32_e32 v32, v54, v38
	v_fmac_f32_e32 v33, v55, v35
	v_fmac_f32_e32 v32, v55, v39
	v_add_f32_e32 v95, v41, v33
	v_add_f32_e32 v96, v40, v32
	ds_read_b128 v[40:43], v60 offset:19456
	s_waitcnt lgkmcnt(1)
	v_mul_f32_e32 v36, v53, v131
	v_fmac_f32_e32 v36, v52, v130
	v_fmac_f32_e32 v36, v54, v132
	v_fmac_f32_e32 v36, v55, v133
	v_add_f32_e32 v97, v45, v36
	ds_read_b128 v[130:133], v60 offset:23552
	s_waitcnt lgkmcnt(1)
	v_mul_f32_e32 v45, v53, v41
	v_fmac_f32_e32 v45, v52, v40
	v_fmac_f32_e32 v45, v54, v42
	v_fmac_f32_e32 v45, v55, v43
	v_add_f32_e32 v125, v44, v45
	ds_read_b128 v[134:137], v60 offset:27648
	s_waitcnt lgkmcnt(1)
	v_mul_f32_e32 v98, v53, v131
	v_fmac_f32_e32 v98, v52, v130
	v_fmac_f32_e32 v98, v54, v132
	v_fmac_f32_e32 v98, v55, v133
	ds_read_b128 v[130:133], v60 offset:31744
	v_add_f32_e32 v124, v124, v98
	s_waitcnt lgkmcnt(1)
	v_mul_f32_e32 v98, v53, v135
	v_fmac_f32_e32 v98, v52, v134
	v_fmac_f32_e32 v98, v54, v136
	v_fmac_f32_e32 v98, v55, v137
	ds_read_b128 v[134:137], v60 offset:35840
	v_add_f32_e32 v98, v123, v98
	s_waitcnt lgkmcnt(1)
	v_mul_f32_e32 v123, v53, v131
	v_fmac_f32_e32 v123, v52, v130
	v_fmac_f32_e32 v123, v54, v132
	v_fmac_f32_e32 v123, v55, v133
	ds_read_b128 v[130:133], v60 offset:39936
	v_add_f32_e32 v122, v122, v123
	s_waitcnt lgkmcnt(1)
	v_mul_f32_e32 v123, v53, v135
	v_fmac_f32_e32 v123, v52, v134
	v_fmac_f32_e32 v123, v54, v136
	v_fmac_f32_e32 v123, v55, v137
	ds_read_b128 v[134:137], v60 offset:44032
	v_add_f32_e32 v111, v111, v123
	s_waitcnt lgkmcnt(1)
	v_mul_f32_e32 v123, v53, v131
	v_fmac_f32_e32 v123, v52, v130
	v_fmac_f32_e32 v123, v54, v132
	v_fmac_f32_e32 v123, v55, v133
	ds_read_b128 v[130:133], v60 offset:48128
	v_add_f32_e32 v110, v110, v123
	s_waitcnt lgkmcnt(1)
	v_mul_f32_e32 v123, v53, v135
	v_fmac_f32_e32 v123, v52, v134
	v_fmac_f32_e32 v123, v54, v136
	v_fmac_f32_e32 v123, v55, v137
	ds_read_b128 v[134:137], v60 offset:52224
	v_add_f32_e32 v109, v109, v123
	s_waitcnt lgkmcnt(1)
	v_mul_f32_e32 v123, v53, v131
	v_fmac_f32_e32 v123, v52, v130
	v_fmac_f32_e32 v123, v54, v132
	v_fmac_f32_e32 v123, v55, v133
	ds_read_b128 v[130:133], v60 offset:56320
	v_add_f32_e32 v108, v108, v123
	s_waitcnt lgkmcnt(1)
	v_mul_f32_e32 v123, v53, v135
	v_fmac_f32_e32 v123, v52, v134
	v_fmac_f32_e32 v123, v54, v136
	v_fmac_f32_e32 v123, v55, v137
	ds_read_b128 v[134:137], v60 offset:60416
	v_add_f32_e32 v103, v103, v123
	s_waitcnt lgkmcnt(1)
	v_mul_f32_e32 v123, v53, v131
	v_fmac_f32_e32 v123, v52, v130
	v_fmac_f32_e32 v123, v54, v132
	v_fmac_f32_e32 v123, v55, v133
	ds_read_b128 v[130:133], v60 offset:64512
	v_add_f32_e32 v102, v102, v123
	s_waitcnt lgkmcnt(1)
	v_mul_f32_e32 v123, v53, v135
	v_fmac_f32_e32 v123, v52, v134
	v_fmac_f32_e32 v123, v54, v136
	v_fmac_f32_e32 v123, v55, v137
	v_add_f32_e32 v123, v100, v123
	s_waitcnt lgkmcnt(0)
	v_mul_f32_e32 v100, v53, v131
	v_fmac_f32_e32 v100, v52, v130
	v_fmac_f32_e32 v100, v54, v132
	v_fmac_f32_e32 v100, v55, v133
	v_add_f32_e32 v129, v101, v100
	v_mov_b32_e32 v100, v48
	v_mov_b32_e32 v101, v52
	v_mov_b32_e32 v52, v49
	v_mov_b32_e32 v48, v218
	v_mov_b32_e32 v126, v214
	v_mov_b32_e32 v130, v222
	v_mov_b32_e32 v127, v230
	v_mov_b32_e32 v49, v238
	v_pk_mul_f32 v[48:49], v[52:53], v[48:49]
	v_mov_b32_e32 v36, v219
	v_pk_fma_f32 v[48:49], v[100:101], v[126:127], v[48:49]
	v_mov_b32_e32 v126, v50
	v_mov_b32_e32 v127, v54
	v_mov_b32_e32 v131, v242
	v_pk_fma_f32 v[48:49], v[126:127], v[130:131], v[48:49]
	v_mov_b32_e32 v54, v51
	v_mov_b32_e32 v50, v226
	v_mov_b32_e32 v51, v246
	v_mov_b32_e32 v32, v215
	v_mov_b32_e32 v37, v239
	v_pk_mul_f32 v[24:25], v[52:53], v[36:37]
	v_pk_fma_f32 v[48:49], v[54:55], v[50:51], v[48:49]
	v_mov_b32_e32 v33, v231
	v_pk_fma_f32 v[24:25], v[100:101], v[32:33], v[24:25]
	v_mov_b32_e32 v40, v223
	v_add_f32_e32 v16, v107, v48
	v_mov_b32_e32 v41, v243
	v_pk_fma_f32 v[20:21], v[126:127], v[40:41], v[24:25]
	v_mov_b32_e32 v44, v227
	v_add_f32_e32 v28, v16, v49
	v_mov_b32_e32 v45, v247
	v_pk_fma_f32 v[16:17], v[54:55], v[44:45], v[20:21]
	v_mov_b32_e32 v20, v220
	v_add_f32_e32 v16, v105, v16
	v_mov_b32_e32 v21, v240
	v_add_f32_e32 v24, v16, v17
	v_mov_b32_e32 v16, v216
	v_mov_b32_e32 v17, v232
	v_pk_mul_f32 v[20:21], v[52:53], v[20:21]
	v_mov_b32_e32 v38, v221
	v_pk_fma_f32 v[16:17], v[100:101], v[16:17], v[20:21]
	v_mov_b32_e32 v20, v224
	v_mov_b32_e32 v21, v244
	v_pk_fma_f32 v[16:17], v[126:127], v[20:21], v[16:17]
	v_mov_b32_e32 v20, v228
	v_mov_b32_e32 v21, v248
	v_pk_fma_f32 v[16:17], v[54:55], v[20:21], v[16:17]
	v_mov_b32_e32 v34, v217
	v_add_f32_e32 v16, v106, v16
	v_add_f32_e32 v20, v16, v17
	v_mov_b32_e32 v39, v241
	v_pk_mul_f32 v[16:17], v[52:53], v[38:39]
	v_mov_b32_e32 v42, v225
	v_mov_b32_e32 v35, v233
	v_pk_fma_f32 v[16:17], v[100:101], v[34:35], v[16:17]
	v_mov_b32_e32 v46, v229
	v_mov_b32_e32 v43, v245
	v_pk_fma_f32 v[16:17], v[126:127], v[42:43], v[16:17]
	v_add_f32_dpp v18, v24, v24 quad_perm:[1,0,3,2] row_mask:0xf bank_mask:0xf bound_ctrl:1
	v_mov_b32_e32 v47, v249
	v_pk_fma_f32 v[16:17], v[54:55], v[46:47], v[16:17]
	v_add_f32_dpp v20, v20, v20 quad_perm:[1,0,3,2] row_mask:0xf bank_mask:0xf bound_ctrl:1
	v_add_f32_e32 v16, v104, v16
	v_add_f32_e32 v22, v16, v17
	v_add_f32_dpp v18, v18, v18 quad_perm:[2,3,0,1] row_mask:0xf bank_mask:0xf bound_ctrl:1
	v_add_f32_dpp v16, v28, v28 quad_perm:[1,0,3,2] row_mask:0xf bank_mask:0xf bound_ctrl:1
	v_add_f32_dpp v20, v20, v20 quad_perm:[2,3,0,1] row_mask:0xf bank_mask:0xf bound_ctrl:1
	v_add_f32_dpp v18, v18, v18 row_half_mirror row_mask:0xf bank_mask:0xf bound_ctrl:1
	v_add_f32_dpp v16, v16, v16 quad_perm:[2,3,0,1] row_mask:0xf bank_mask:0xf bound_ctrl:1
	v_add_f32_dpp v20, v20, v20 row_half_mirror row_mask:0xf bank_mask:0xf bound_ctrl:1
	v_add_f32_dpp v18, v18, v18 row_mirror row_mask:0xf bank_mask:0xf bound_ctrl:1
	v_add_f32_dpp v16, v16, v16 row_half_mirror row_mask:0xf bank_mask:0xf bound_ctrl:1
	v_add_f32_dpp v20, v20, v20 row_mirror row_mask:0xf bank_mask:0xf bound_ctrl:1
	s_nop 0
	v_add_f32_dpp v16, v16, v16 row_mirror row_mask:0xf bank_mask:0xf bound_ctrl:1
	s_nop 0
	v_readlane_b32 s2, v16, 16
	v_readlane_b32 s4, v16, 48
	v_readlane_b32 s0, v16, 0
	v_readlane_b32 s1, v16, 32
	v_mov_b32_e32 v16, s2
	v_mov_b32_e32 v17, s4
	v_readlane_b32 s2, v18, 16
	v_readlane_b32 s4, v18, 48
	v_pk_add_f32 v[16:17], s[0:1], v[16:17]
	v_readlane_b32 s0, v18, 0
	v_readlane_b32 s1, v18, 32
	v_mov_b32_e32 v18, s2
	v_mov_b32_e32 v19, s4
	v_readlane_b32 s2, v20, 16
	v_readlane_b32 s4, v20, 48
	v_pk_add_f32 v[18:19], s[0:1], v[18:19]
	v_readlane_b32 s0, v20, 0
	v_readlane_b32 s1, v20, 32
	v_mov_b32_e32 v20, s2
	v_mov_b32_e32 v21, s4
	v_pk_add_f32 v[20:21], s[0:1], v[20:21]
	v_mov_b32_e32 v25, v18
	v_add_f32_e32 v26, v20, v21
	v_add_f32_dpp v20, v22, v22 quad_perm:[1,0,3,2] row_mask:0xf bank_mask:0xf bound_ctrl:1
	v_mov_b32_e32 v18, v17
	s_nop 0
	v_add_f32_dpp v20, v20, v20 quad_perm:[2,3,0,1] row_mask:0xf bank_mask:0xf bound_ctrl:1
	s_nop 1
	v_add_f32_dpp v20, v20, v20 row_half_mirror row_mask:0xf bank_mask:0xf bound_ctrl:1
	s_nop 1
	v_add_f32_dpp v20, v20, v20 row_mirror row_mask:0xf bank_mask:0xf bound_ctrl:1
	s_nop 0
	v_readlane_b32 s2, v20, 16
	v_readlane_b32 s4, v20, 48
	v_readlane_b32 s0, v20, 0
	v_readlane_b32 s1, v20, 32
	v_mov_b32_e32 v20, s2
	v_mov_b32_e32 v21, s4
	v_pk_add_f32 v[20:21], s[0:1], v[20:21]
	s_nop 0
	v_add_f32_e32 v27, v20, v21
	v_add_f32_dpp v20, v94, v94 quad_perm:[1,0,3,2] row_mask:0xf bank_mask:0xf bound_ctrl:1
	s_nop 1
	v_add_f32_dpp v20, v20, v20 quad_perm:[2,3,0,1] row_mask:0xf bank_mask:0xf bound_ctrl:1
	s_nop 1
	v_add_f32_dpp v20, v20, v20 row_half_mirror row_mask:0xf bank_mask:0xf bound_ctrl:1
	s_nop 1
	v_add_f32_dpp v20, v20, v20 row_mirror row_mask:0xf bank_mask:0xf bound_ctrl:1
	s_nop 0
	v_readlane_b32 s20, v20, 0
	v_readlane_b32 s4, v20, 16
	v_readlane_b32 s21, v20, 32
	v_readlane_b32 s5, v20, 48
	v_add_f32_dpp v20, v95, v95 quad_perm:[1,0,3,2] row_mask:0xf bank_mask:0xf bound_ctrl:1
	s_nop 1
	v_add_f32_dpp v20, v20, v20 quad_perm:[2,3,0,1] row_mask:0xf bank_mask:0xf bound_ctrl:1
	s_nop 1
	v_add_f32_dpp v20, v20, v20 row_half_mirror row_mask:0xf bank_mask:0xf bound_ctrl:1
	s_nop 1
	v_add_f32_dpp v20, v20, v20 row_mirror row_mask:0xf bank_mask:0xf bound_ctrl:1
	s_nop 0
	v_readlane_b32 s91, v20, 0
	v_readlane_b32 s95, v20, 16
	v_readlane_b32 s94, v20, 32
	v_readlane_b32 s92, v20, 48
	v_add_f32_dpp v20, v96, v96 quad_perm:[1,0,3,2] row_mask:0xf bank_mask:0xf bound_ctrl:1
	s_nop 1
	v_add_f32_dpp v20, v20, v20 quad_perm:[2,3,0,1] row_mask:0xf bank_mask:0xf bound_ctrl:1
	s_nop 1
	v_add_f32_dpp v20, v20, v20 row_half_mirror row_mask:0xf bank_mask:0xf bound_ctrl:1
	s_nop 1
	v_add_f32_dpp v20, v20, v20 row_mirror row_mask:0xf bank_mask:0xf bound_ctrl:1
	s_nop 0
	v_readlane_b32 s6, v20, 0
	v_readlane_b32 s75, v20, 16
	v_readlane_b32 s74, v20, 32
	v_readlane_b32 s84, v20, 48
	v_add_f32_dpp v20, v97, v97 quad_perm:[1,0,3,2] row_mask:0xf bank_mask:0xf bound_ctrl:1
	s_nop 1
	v_add_f32_dpp v20, v20, v20 quad_perm:[2,3,0,1] row_mask:0xf bank_mask:0xf bound_ctrl:1
	s_nop 1
	v_add_f32_dpp v20, v20, v20 row_half_mirror row_mask:0xf bank_mask:0xf bound_ctrl:1
	s_nop 1
	v_add_f32_dpp v20, v20, v20 row_mirror row_mask:0xf bank_mask:0xf bound_ctrl:1
	s_nop 0
	v_readlane_b32 s97, v20, 0
	v_readlane_b32 s9, v20, 16
	v_readlane_b32 s8, v20, 32
	v_readlane_b32 s12, v20, 48
	v_add_f32_dpp v20, v125, v125 quad_perm:[1,0,3,2] row_mask:0xf bank_mask:0xf bound_ctrl:1
	s_nop 1
	v_add_f32_dpp v20, v20, v20 quad_perm:[2,3,0,1] row_mask:0xf bank_mask:0xf bound_ctrl:1
	s_nop 1
	v_add_f32_dpp v20, v20, v20 row_half_mirror row_mask:0xf bank_mask:0xf bound_ctrl:1
	s_nop 1
	v_add_f32_dpp v20, v20, v20 row_mirror row_mask:0xf bank_mask:0xf bound_ctrl:1
	s_nop 0
	v_readlane_b32 s59, v20, 0
	v_readlane_b32 s61, v20, 16
	v_readlane_b32 s60, v20, 32
	v_readlane_b32 s82, v20, 48
	v_add_f32_dpp v20, v124, v124 quad_perm:[1,0,3,2] row_mask:0xf bank_mask:0xf bound_ctrl:1
	s_nop 1
	v_add_f32_dpp v20, v20, v20 quad_perm:[2,3,0,1] row_mask:0xf bank_mask:0xf bound_ctrl:1
	s_nop 1
	v_add_f32_dpp v20, v20, v20 row_half_mirror row_mask:0xf bank_mask:0xf bound_ctrl:1
	s_nop 1
	v_add_f32_dpp v24, v20, v20 row_mirror row_mask:0xf bank_mask:0xf bound_ctrl:1
	s_nop 0
	v_readlane_b32 s52, v24, 0
	v_readlane_b32 s54, v24, 16
	v_readlane_b32 s53, v24, 32
	v_readlane_b32 s93, v24, 48
	v_add_f32_dpp v24, v98, v98 quad_perm:[1,0,3,2] row_mask:0xf bank_mask:0xf bound_ctrl:1
	s_nop 1
	v_add_f32_dpp v24, v24, v24 quad_perm:[2,3,0,1] row_mask:0xf bank_mask:0xf bound_ctrl:1
	s_nop 1
	v_add_f32_dpp v24, v24, v24 row_half_mirror row_mask:0xf bank_mask:0xf bound_ctrl:1
	s_nop 1
	v_add_f32_dpp v24, v24, v24 row_mirror row_mask:0xf bank_mask:0xf bound_ctrl:1
	s_nop 0
	v_readlane_b32 s85, v24, 0
	v_readlane_b32 s87, v24, 16
	v_readlane_b32 s86, v24, 32
	v_readlane_b32 s90, v24, 48
	v_add_f32_dpp v24, v122, v122 quad_perm:[1,0,3,2] row_mask:0xf bank_mask:0xf bound_ctrl:1
	s_nop 1
	v_add_f32_dpp v24, v24, v24 quad_perm:[2,3,0,1] row_mask:0xf bank_mask:0xf bound_ctrl:1
	s_nop 1
	v_add_f32_dpp v24, v24, v24 row_half_mirror row_mask:0xf bank_mask:0xf bound_ctrl:1
	s_nop 1
	v_add_f32_dpp v24, v24, v24 row_mirror row_mask:0xf bank_mask:0xf bound_ctrl:1
	s_nop 0
	v_readlane_b32 s13, v24, 0
	v_readlane_b32 s24, v24, 16
	v_readlane_b32 s16, v24, 32
	v_readlane_b32 s17, v24, 48
	v_add_f32_dpp v24, v111, v111 quad_perm:[1,0,3,2] row_mask:0xf bank_mask:0xf bound_ctrl:1
	s_nop 1
	v_add_f32_dpp v24, v24, v24 quad_perm:[2,3,0,1] row_mask:0xf bank_mask:0xf bound_ctrl:1
	s_nop 1
	v_add_f32_dpp v24, v24, v24 row_half_mirror row_mask:0xf bank_mask:0xf bound_ctrl:1
	s_nop 1
	v_add_f32_dpp v24, v24, v24 row_mirror row_mask:0xf bank_mask:0xf bound_ctrl:1
	s_nop 0
	v_readlane_b32 s83, v24, 0
	v_readlane_b32 s89, v24, 16
	v_readlane_b32 s88, v24, 32
	v_readlane_b32 s96, v24, 48
	v_add_f32_dpp v24, v110, v110 quad_perm:[1,0,3,2] row_mask:0xf bank_mask:0xf bound_ctrl:1
	s_nop 1
	v_add_f32_dpp v24, v24, v24 quad_perm:[2,3,0,1] row_mask:0xf bank_mask:0xf bound_ctrl:1
	s_nop 1
	v_add_f32_dpp v24, v24, v24 row_half_mirror row_mask:0xf bank_mask:0xf bound_ctrl:1
	s_nop 1
	v_add_f32_dpp v24, v24, v24 row_mirror row_mask:0xf bank_mask:0xf bound_ctrl:1
	s_nop 0
	v_readlane_b32 s55, v24, 0
	v_readlane_b32 s57, v24, 16
	v_readlane_b32 s56, v24, 32
	v_readlane_b32 s58, v24, 48
	v_add_f32_dpp v24, v109, v109 quad_perm:[1,0,3,2] row_mask:0xf bank_mask:0xf bound_ctrl:1
	s_nop 1
	v_add_f32_dpp v24, v24, v24 quad_perm:[2,3,0,1] row_mask:0xf bank_mask:0xf bound_ctrl:1
	s_nop 1
	v_add_f32_dpp v24, v24, v24 row_half_mirror row_mask:0xf bank_mask:0xf bound_ctrl:1
	s_nop 1
	v_add_f32_dpp v24, v24, v24 row_mirror row_mask:0xf bank_mask:0xf bound_ctrl:1
	s_nop 0
	v_readlane_b32 s46, v24, 0
	v_readlane_b32 s48, v24, 16
	v_readlane_b32 s47, v24, 32
	v_readlane_b32 s49, v24, 48
	v_add_f32_dpp v24, v108, v108 quad_perm:[1,0,3,2] row_mask:0xf bank_mask:0xf bound_ctrl:1
	s_nop 1
	v_add_f32_dpp v24, v24, v24 quad_perm:[2,3,0,1] row_mask:0xf bank_mask:0xf bound_ctrl:1
	s_nop 1
	v_add_f32_dpp v24, v24, v24 row_half_mirror row_mask:0xf bank_mask:0xf bound_ctrl:1
	s_nop 1
	v_add_f32_dpp v24, v24, v24 row_mirror row_mask:0xf bank_mask:0xf bound_ctrl:1
	s_nop 0
	v_readlane_b32 s38, v24, 0
	v_readlane_b32 s40, v24, 16
	v_readlane_b32 s39, v24, 32
	v_readlane_b32 s41, v24, 48
	v_add_f32_dpp v24, v103, v103 quad_perm:[1,0,3,2] row_mask:0xf bank_mask:0xf bound_ctrl:1
	s_nop 1
	v_add_f32_dpp v24, v24, v24 quad_perm:[2,3,0,1] row_mask:0xf bank_mask:0xf bound_ctrl:1
	s_nop 1
	v_add_f32_dpp v24, v24, v24 row_half_mirror row_mask:0xf bank_mask:0xf bound_ctrl:1
	s_nop 1
	v_add_f32_dpp v24, v24, v24 row_mirror row_mask:0xf bank_mask:0xf bound_ctrl:1
	s_nop 0
	v_readlane_b32 s34, v24, 0
	v_readlane_b32 s36, v24, 16
	v_readlane_b32 s35, v24, 32
	v_readlane_b32 s37, v24, 48
	v_add_f32_dpp v24, v102, v102 quad_perm:[1,0,3,2] row_mask:0xf bank_mask:0xf bound_ctrl:1
	s_nop 1
	v_add_f32_dpp v24, v24, v24 quad_perm:[2,3,0,1] row_mask:0xf bank_mask:0xf bound_ctrl:1
	s_nop 1
	v_add_f32_dpp v24, v24, v24 row_half_mirror row_mask:0xf bank_mask:0xf bound_ctrl:1
	s_nop 1
	v_add_f32_dpp v24, v24, v24 row_mirror row_mask:0xf bank_mask:0xf bound_ctrl:1
	s_nop 0
	v_readlane_b32 s29, v24, 0
	v_readlane_b32 s31, v24, 16
	v_readlane_b32 s30, v24, 32
	v_readlane_b32 s33, v24, 48
	v_add_f32_dpp v24, v123, v123 quad_perm:[1,0,3,2] row_mask:0xf bank_mask:0xf bound_ctrl:1
	s_nop 1
	v_add_f32_dpp v24, v24, v24 quad_perm:[2,3,0,1] row_mask:0xf bank_mask:0xf bound_ctrl:1
	s_nop 1
	v_add_f32_dpp v24, v24, v24 row_half_mirror row_mask:0xf bank_mask:0xf bound_ctrl:1
	s_nop 1
	v_add_f32_dpp v28, v24, v24 row_mirror row_mask:0xf bank_mask:0xf bound_ctrl:1
	v_add_f32_dpp v24, v129, v129 quad_perm:[1,0,3,2] row_mask:0xf bank_mask:0xf bound_ctrl:1
	v_readlane_b32 s25, v28, 0
	v_readlane_b32 s28, v28, 16
	v_add_f32_dpp v24, v24, v24 quad_perm:[2,3,0,1] row_mask:0xf bank_mask:0xf bound_ctrl:1
	v_readlane_b32 s50, v28, 32
	v_readlane_b32 s51, v28, 48
	v_add_f32_dpp v24, v24, v24 row_half_mirror row_mask:0xf bank_mask:0xf bound_ctrl:1
	s_nop 1
	v_add_f32_dpp v29, v24, v24 row_mirror row_mask:0xf bank_mask:0xf bound_ctrl:1
	v_mov_b32_e32 v24, v16
	v_pk_add_f32 v[16:17], v[24:25], v[18:19]
	v_mov_b32_e32 v20, v178
	v_mov_b32_e32 v21, v179
	v_mov_b32_e32 v22, v180
	v_mov_b32_e32 v23, v181
	v_add_f32_e32 v19, v26, v22
	v_pk_add_f32 v[16:17], v[16:17], v[20:21]
	v_add_f32_e32 v18, v27, v23
	v_cmp_gt_f32_e32 vcc, v17, v16
	v_mov_b32_e32 v22, 0
	v_readlane_b32 s42, v29, 0
	v_cndmask_b32_e32 v20, v16, v17, vcc
	v_cmp_gt_f32_e64 s[18:19], v19, v20
	v_cndmask_b32_e64 v21, 0, 1, vcc
	s_and_b64 s[14:15], s[18:19], exec
	v_cndmask_b32_e64 v20, v20, v19, s[18:19]
	v_cmp_ngt_f32_e64 s[0:1], v18, v20
	v_readfirstlane_b32 s2, v21
	s_cselect_b32 s2, 2, s2
	s_and_b64 s[14:15], s[0:1], exec
	s_cselect_b32 s2, s2, 3
	s_cmp_eq_u32 s2, 0
	s_cselect_b64 s[26:27], -1, 0
	s_cmp_lg_u32 s2, 0
	v_mov_b32_e32 v21, 0
	v_readlane_b32 s44, v29, 16
	v_readlane_b32 s43, v29, 32
	v_readlane_b32 s45, v29, 48
	v_cmp_gt_f32_e64 s[14:15], v18, v20
	s_waitcnt lgkmcnt(0)
	s_cbranch_scc0 .LBB0_560
	v_cndmask_b32_e64 v23, 0, 1, s[26:27]
	v_cmp_ne_u32_e64 s[20:21], 1, v23
	s_andn2_b64 vcc, exec, s[26:27]
	s_cbranch_vccz .LBB0_561

.LBB0_1669:
	s_or_b64 exec, exec, s[0:1]
	s_add_u32 s0, s70, 0x10000
	s_waitcnt vmcnt(17)
	v_mov_b32_e32 v56, v128
	s_waitcnt lgkmcnt(0)
	s_barrier
	s_addc_u32 s1, s71, 0
	s_nop 0
	v_ashrrev_i32_e32 v57, 31, v56
	v_add_u32_e32 v66, 0x100, v56
	v_lshl_add_u64 v[8:9], v[56:57], 4, s[0:1]
	v_ashrrev_i32_e32 v67, 31, v66
	v_add_u32_e32 v68, 0x200, v56
	v_add_u32_e32 v70, 0x300, v56
	s_barrier
	v_lshl_add_u64 v[10:11], v[66:67], 4, s[0:1]
	global_load_dwordx4 v[0:3], v[8:9], off
	global_load_dwordx4 v[4:7], v[10:11], off
	v_ashrrev_i32_e32 v69, 31, v68
	v_ashrrev_i32_e32 v71, 31, v70
	v_lshl_add_u64 v[8:9], v[68:69], 4, s[0:1]
	v_lshl_add_u64 v[12:13], v[70:71], 4, s[0:1]
	v_add_u32_e32 v72, 0x400, v56
	global_load_dwordx4 v[8:11], v[8:9], off
	v_ashrrev_i32_e32 v73, 31, v72
	global_load_dwordx4 v[12:15], v[12:13], off
	v_lshl_add_u64 v[16:17], v[72:73], 4, s[0:1]
	v_add_u32_e32 v74, 0x500, v56
	global_load_dwordx4 v[16:19], v[16:17], off
	v_ashrrev_i32_e32 v75, 31, v74
	v_lshl_add_u64 v[20:21], v[74:75], 4, s[0:1]
	v_add_u32_e32 v76, 0x600, v56
	global_load_dwordx4 v[20:23], v[20:21], off
	v_ashrrev_i32_e32 v77, 31, v76
	v_lshl_add_u64 v[24:25], v[76:77], 4, s[0:1]
	v_add_u32_e32 v78, 0x700, v56
	global_load_dwordx4 v[24:27], v[24:25], off
	v_ashrrev_i32_e32 v79, 31, v78
	v_lshl_add_u64 v[28:29], v[78:79], 4, s[0:1]
	v_add_u32_e32 v80, 0x800, v56
	global_load_dwordx4 v[28:31], v[28:29], off
	v_ashrrev_i32_e32 v81, 31, v80
	v_lshl_add_u64 v[32:33], v[80:81], 4, s[0:1]
	v_add_u32_e32 v82, 0x900, v56
	global_load_dwordx4 v[32:35], v[32:33], off
	v_ashrrev_i32_e32 v83, 31, v82
	v_lshl_add_u64 v[36:37], v[82:83], 4, s[0:1]
	v_add_u32_e32 v84, 0xa00, v56
	global_load_dwordx4 v[36:39], v[36:37], off
	v_ashrrev_i32_e32 v85, 31, v84
	v_lshl_add_u64 v[40:41], v[84:85], 4, s[0:1]
	v_add_u32_e32 v86, 0xb00, v56
	global_load_dwordx4 v[40:43], v[40:41], off
	v_ashrrev_i32_e32 v87, 31, v86
	v_lshl_add_u64 v[44:45], v[86:87], 4, s[0:1]
	v_add_u32_e32 v88, 0xc00, v56
	global_load_dwordx4 v[44:47], v[44:45], off
	v_ashrrev_i32_e32 v89, 31, v88
	v_lshl_add_u64 v[48:49], v[88:89], 4, s[0:1]
	v_add_u32_e32 v90, 0xd00, v56
	global_load_dwordx4 v[48:51], v[48:49], off
	v_ashrrev_i32_e32 v91, 31, v90
	v_lshl_add_u64 v[52:53], v[90:91], 4, s[0:1]
	v_add_u32_e32 v92, 0xe00, v56
	global_load_dwordx4 v[52:55], v[52:53], off
	v_ashrrev_i32_e32 v93, 31, v92
	v_lshl_add_u64 v[58:59], v[92:93], 4, s[0:1]
	v_add_u32_e32 v94, 0xf00, v56
	global_load_dwordx4 v[58:61], v[58:59], off
	v_ashrrev_i32_e32 v95, 31, v94
	s_waitcnt vmcnt(31)
	v_lshl_add_u64 v[62:63], v[94:95], 4, s[0:1]
	global_load_dwordx4 v[62:65], v[62:63], off
	v_lshlrev_b32_e32 v67, 14, v56
	v_and_b32_e32 v69, -4, v56
	v_and_b32_e32 v67, 0xc000, v67
	v_and_b32_e32 v66, -4, v66
	v_and_b32_e32 v68, -4, v68
	v_add_u32_e32 v69, v67, v69
	v_add_u32_e32 v66, v67, v66
	v_add_u32_e32 v68, v67, v68
	v_readlane_b32 s0, v237, 46
	v_readlane_b32 s1, v237, 47
	s_andn2_b64 vcc, exec, s[0:1]
	s_waitcnt vmcnt(15)
	ds_write2st64_b32 v69, v0, v1 offset1:16
	ds_write2st64_b32 v69, v2, v3 offset0:32 offset1:48
	s_waitcnt vmcnt(14)
	ds_write2st64_b32 v66, v4, v5 offset1:16
	ds_write2st64_b32 v66, v6, v7 offset0:32 offset1:48
	s_waitcnt vmcnt(13)
	ds_write2st64_b32 v68, v8, v9 offset1:16
	ds_write2st64_b32 v68, v10, v11 offset0:32 offset1:48
	v_and_b32_e32 v0, -4, v70
	v_add_u32_e32 v0, v67, v0
	s_waitcnt vmcnt(12)
	ds_write2st64_b32 v0, v12, v13 offset1:16
	ds_write2st64_b32 v0, v14, v15 offset0:32 offset1:48
	v_and_b32_e32 v0, -4, v72
	v_add_u32_e32 v0, v67, v0
	s_waitcnt vmcnt(11)
	ds_write2st64_b32 v0, v16, v17 offset1:16
	ds_write2st64_b32 v0, v18, v19 offset0:32 offset1:48
	v_and_b32_e32 v0, -4, v74
	v_add_u32_e32 v0, v67, v0
	s_waitcnt vmcnt(10)
	ds_write2st64_b32 v0, v20, v21 offset1:16
	ds_write2st64_b32 v0, v22, v23 offset0:32 offset1:48
	v_and_b32_e32 v0, -4, v76
	v_add_u32_e32 v0, v67, v0
	s_waitcnt vmcnt(9)
	ds_write2st64_b32 v0, v24, v25 offset1:16
	ds_write2st64_b32 v0, v26, v27 offset0:32 offset1:48
	v_and_b32_e32 v0, -4, v78
	v_add_u32_e32 v0, v67, v0
	s_waitcnt vmcnt(8)
	ds_write2st64_b32 v0, v28, v29 offset1:16
	ds_write2st64_b32 v0, v30, v31 offset0:32 offset1:48
	v_and_b32_e32 v0, -4, v80
	v_add_u32_e32 v0, v67, v0
	s_waitcnt vmcnt(7)
	ds_write2st64_b32 v0, v32, v33 offset1:16
	ds_write2st64_b32 v0, v34, v35 offset0:32 offset1:48
	v_and_b32_e32 v0, -4, v82
	v_add_u32_e32 v0, v67, v0
	s_waitcnt vmcnt(6)
	ds_write2st64_b32 v0, v36, v37 offset1:16
	ds_write2st64_b32 v0, v38, v39 offset0:32 offset1:48
	v_and_b32_e32 v0, -4, v84
	v_add_u32_e32 v0, v67, v0
	s_waitcnt vmcnt(5)
	ds_write2st64_b32 v0, v40, v41 offset1:16
	ds_write2st64_b32 v0, v42, v43 offset0:32 offset1:48
	v_and_b32_e32 v0, -4, v86
	v_add_u32_e32 v0, v67, v0
	s_waitcnt vmcnt(4)
	ds_write2st64_b32 v0, v44, v45 offset1:16
	ds_write2st64_b32 v0, v46, v47 offset0:32 offset1:48
	v_and_b32_e32 v0, -4, v88
	v_add_u32_e32 v0, v67, v0
	s_waitcnt vmcnt(3)
	ds_write2st64_b32 v0, v48, v49 offset1:16
	ds_write2st64_b32 v0, v50, v51 offset0:32 offset1:48
	v_and_b32_e32 v0, -4, v90
	v_add_u32_e32 v0, v67, v0
	s_waitcnt vmcnt(2)
	ds_write2st64_b32 v0, v52, v53 offset1:16
	ds_write2st64_b32 v0, v54, v55 offset0:32 offset1:48
	v_and_b32_e32 v0, -4, v92
	v_add_u32_e32 v0, v67, v0
	s_waitcnt vmcnt(1)
	ds_write2st64_b32 v0, v58, v59 offset1:16
	ds_write2st64_b32 v0, v60, v61 offset0:32 offset1:48
	v_and_b32_e32 v0, -4, v94
	v_add_u32_e32 v0, v67, v0
	s_waitcnt vmcnt(0)
	ds_write2st64_b32 v0, v62, v63 offset1:16
	ds_write2st64_b32 v0, v64, v65 offset0:32 offset1:48
	s_waitcnt lgkmcnt(0)
	s_barrier
	s_cbranch_vccnz .LBB0_1718
	v_and_b32_e32 v5, 63, v56
	v_readlane_b32 s8, v237, 48
	v_lshlrev_b32_e32 v60, 4, v5
	v_mov_b32_e32 v61, 0
	v_readlane_b32 s12, v237, 52
	v_readlane_b32 s13, v237, 53
	v_readlane_b32 s14, v237, 54
	v_readlane_b32 s15, v237, 55
	v_lshl_add_u64 v[2:3], s[62:63], 0, v[60:61]
	s_mov_b64 s[0:1], 0x1000
	v_lshl_add_u64 v[62:63], s[14:15], 0, v[60:61]
	v_readlane_b32 s12, v237, 56
	v_lshl_add_u64 v[66:67], v[2:3], 0, s[0:1]
	v_lshl_add_u64 v[2:3], s[64:65], 0, v[60:61]
	v_readlane_b32 s13, v237, 57
	v_lshl_add_u64 v[68:69], v[2:3], 0, s[0:1]
	v_lshrrev_b32_e32 v250, 6, v56
	v_lshlrev_b32_e32 v250, 10, v250
	v_mov_b32_e32 v251, 0
	v_lshl_add_u64 v[252:253], v[66:67], 0, v[250:251]
	global_load_dwordx4 v[186:189], v[252:253], off
	v_lshl_add_u64 v[252:253], v[68:69], 0, v[250:251]
	global_load_dwordx4 v[190:193], v[252:253], off
	v_lshlrev_b32_e32 v250, 4, v56
	v_add_u32_e32 v250, 0x10400, v250
	s_waitcnt vmcnt(0)
	ds_write_b128 v250, v[186:189]
	ds_write_b128 v250, v[190:193] offset:4096
	v_add_u32_e32 v234, 0x10400, v60
	s_waitcnt lgkmcnt(0)
	s_mov_b64 s[0:1], 0x3d00080
	v_lshl_add_u64 v[2:3], v[56:57], 2, s[12:13]
	v_lshl_add_u64 v[70:71], v[2:3], 0, s[0:1]
	v_lshlrev_b32_e32 v2, 6, v5
	v_mov_b32_e32 v3, v61
	v_lshl_add_u64 v[2:3], s[66:67], 0, v[2:3]
	s_mov_b64 s[0:1], 0x4000
	v_lshl_add_u64 v[72:73], v[2:3], 0, s[0:1]
	s_mov_b64 s[0:1], 0x5000
	v_lshl_add_u64 v[74:75], v[2:3], 0, s[0:1]
	s_mov_b64 s[0:1], 0x6000
	v_lshl_add_u64 v[76:77], v[2:3], 0, s[0:1]
	s_mov_b64 s[0:1], 0x7000
	v_lshl_add_u64 v[78:79], v[2:3], 0, s[0:1]
	v_readlane_b32 s0, v237, 31
	v_ashrrev_i32_e32 v4, 2, v56
	v_lshlrev_b32_e32 v0, 3, v5
	v_mov_b32_e32 v1, v61
	v_readlane_b32 s1, v237, 32
	v_lshlrev_b32_e32 v6, 2, v56
	v_and_b32_e32 v58, -16, v4
	v_readlane_b32 s9, v237, 49
	v_lshl_add_u64 v[64:65], s[46:47], 0, v[0:1]
	v_readlane_b32 s14, v237, 58
	s_mov_b32 s2, s0
	s_lshl_b32 s18, s0, 6
	v_mov_b32_e32 v2, 0x10000
	v_lshl_add_u64 v[0:1], s[12:13], 0, v[0:1]
	s_mov_b64 s[0:1], 0x4500400
	v_cmp_gt_i32_e64 s[4:5], 24, v56
	v_add_u32_e32 v99, 0x10100, v6
	v_ashrrev_i32_e32 v59, 31, v58
	s_mov_b32 s3, 0
	v_cmp_eq_u32_e64 s[6:7], 0, v5
	v_cmp_gt_i32_e64 s[8:9], 64, v56
	v_add_u32_e32 v112, 0x10000, v6
	v_add_u32_e32 v113, 0x10200, v6
	v_add_u32_e32 v57, 0x10180, v6
	v_add_u32_e32 v114, s18, v4
	s_lshl_b32 s16, s14, 6
	v_lshl_add_u32 v115, v4, 2, v2
	v_lshl_add_u64 v[80:81], v[0:1], 0, s[0:1]
	s_mov_b32 s20, 0x3fb504f3
	v_mov_b32_e32 v116, 0x3727c5ac
	v_mov_b32_e32 v117, 1
	v_mov_b32_e32 v118, 0xff61b1e6
	v_mov_b32_e32 v119, 0x10100
	v_mov_b32_e32 v120, 0x10180
	s_mov_b32 s17, s2
	v_readlane_b32 s10, v237, 50
	v_readlane_b32 s11, v237, 51
	v_readlane_b32 s15, v237, 59
	s_branch .LBB0_1672

.LBB0_1672:
	s_barrier
	s_and_saveexec_b64 s[0:1], s[4:5]
	ds_write_b32 v99, v61
	s_or_b64 exec, exec, s[0:1]
	s_lshl_b32 s22, s17, 6
	s_ashr_i32 s23, s22, 31
	v_lshl_add_u64 v[82:83], s[22:23], 0, v[58:59]
	v_lshlrev_b64 v[0:1], 12, v[82:83]
	v_lshl_add_u64 v[0:1], v[62:63], 0, v[0:1]
	v_lshlrev_b64 v[2:3], 11, v[82:83]
	v_lshl_add_u64 v[2:3], v[64:65], 0, v[2:3]
	global_load_dwordx4 v[28:31], v[0:1], off
	global_load_dwordx4 v[20:23], v[0:1], off offset:1024
	global_load_dwordx4 v[24:27], v[0:1], off offset:2048
	global_load_dwordx4 v[16:19], v[0:1], off offset:3072
	global_load_dwordx2 v[84:85], v[2:3], off
	global_load_dwordx2 v[88:89], v[2:3], off offset:512
	global_load_dwordx2 v[90:91], v[2:3], off offset:1024
	global_load_dwordx2 v[92:93], v[2:3], off offset:1536
	global_load_dwordx4 v[182:185], v[72:73], off
	global_load_dwordx4 v[186:189], v[72:73], off offset:16
	global_load_dwordx4 v[190:193], v[72:73], off offset:32
	global_load_dwordx4 v[194:197], v[72:73], off offset:48
	global_load_dwordx4 v[198:201], v[74:75], off
	global_load_dwordx4 v[202:205], v[74:75], off offset:16
	global_load_dwordx4 v[206:209], v[74:75], off offset:32
	global_load_dwordx4 v[210:213], v[74:75], off offset:48
	global_load_dwordx4 v[214:217], v[76:77], off
	global_load_dwordx4 v[218:221], v[76:77], off offset:16
	global_load_dwordx4 v[222:225], v[76:77], off offset:32
	global_load_dwordx4 v[226:229], v[76:77], off offset:48
	global_load_dwordx4 v[230:233], v[78:79], off
	global_load_dwordx4 v[238:241], v[78:79], off offset:16
	global_load_dwordx4 v[242:245], v[78:79], off offset:32
	global_load_dwordx4 v[246:249], v[78:79], off offset:48
	global_load_dword v162, v61, s[72:73] offset:64
	global_load_dword v163, v61, s[72:73] offset:68
	global_load_dword v164, v61, s[72:73] offset:72
	global_load_dword v165, v61, s[72:73] offset:76
	global_load_dword v166, v61, s[72:73] offset:80
	global_load_dword v167, v61, s[72:73] offset:84
	global_load_dword v168, v61, s[72:73] offset:88
	global_load_dword v169, v61, s[72:73] offset:92
	global_load_dword v170, v61, s[72:73] offset:96
	global_load_dword v171, v61, s[72:73] offset:100
	global_load_dword v172, v61, s[72:73] offset:104
	global_load_dword v173, v61, s[72:73] offset:108
	global_load_dword v174, v61, s[72:73] offset:112
	global_load_dword v175, v61, s[72:73] offset:116
	global_load_dword v176, v61, s[72:73] offset:120
	global_load_dword v177, v61, s[72:73] offset:124
	global_load_dwordx4 v[178:181], v61, s[68:69] offset:16
	s_ashr_i32 s19, s18, 31
	v_lshl_add_u64 v[0:1], v[58:59], 0, s[18:19]
	v_lshlrev_b64 v[0:1], 11, v[0:1]
	v_lshl_add_u64 v[86:87], v[80:81], 0, v[0:1]
	s_mov_b32 s19, 0
	v_mov_b32_e32 v121, v115
	s_branch .LBB0_1676

.LBB0_1676:
	s_add_i32 s21, s19, 1
	s_waitcnt vmcnt(0)
	v_mov_b64_e32 v[38:39], v[84:85]
	v_mov_b64_e32 v[32:33], v[92:93]
	v_mov_b64_e32 v[34:35], v[90:91]
	v_mov_b64_e32 v[36:37], v[88:89]
	v_mov_b32_e32 v0, s21
	v_min_u32_e32 v0, 15, v0
	v_mov_b32_e32 v1, 0
	v_lshl_add_u64 v[0:1], v[82:83], 0, v[0:1]
	v_lshlrev_b64 v[2:3], 12, v[0:1]
	v_lshlrev_b64 v[0:1], 11, v[0:1]
	v_lshl_add_u64 v[12:13], v[62:63], 0, v[2:3]
	v_lshl_add_u64 v[92:93], v[64:65], 0, v[0:1]
	global_load_dwordx4 v[0:3], v[12:13], off
	global_load_dwordx2 v[84:85], v[92:93], off
	global_load_dwordx4 v[4:7], v[12:13], off offset:1024
	global_load_dwordx2 v[88:89], v[92:93], off offset:512
	global_load_dwordx4 v[8:11], v[12:13], off offset:2048
	global_load_dwordx2 v[90:91], v[92:93], off offset:1024
	s_nop 0
	global_load_dwordx4 v[12:15], v[12:13], off offset:3072
	s_nop 0
	global_load_dwordx2 v[92:93], v[92:93], off offset:1536
	v_lshlrev_b32_e32 v40, 16, v38
	v_and_b32_e32 v41, 0xffff0000, v38
	v_lshlrev_b32_e32 v38, 16, v39
	v_and_b32_e32 v39, 0xffff0000, v39
	v_lshlrev_b32_e32 v54, 16, v36
	v_and_b32_e32 v55, 0xffff0000, v36
	v_lshlrev_b32_e32 v94, 16, v37
	v_and_b32_e32 v95, 0xffff0000, v37
	v_lshlrev_b32_e32 v96, 16, v34
	v_and_b32_e32 v97, 0xffff0000, v34
	v_lshlrev_b32_e32 v100, 16, v35
	v_and_b32_e32 v101, 0xffff0000, v35
	v_lshlrev_b32_e32 v102, 16, v32
	v_and_b32_e32 v103, 0xffff0000, v32
	v_lshlrev_b32_e32 v104, 16, v33
	v_and_b32_e32 v105, 0xffff0000, v33
	v_pk_fma_f32 v[106:107], v[30:31], s[20:21], v[38:39] op_sel_hi:[1,0,1]
	ds_read_b128 v[30:33], v234
	ds_read_b128 v[34:37], v234 offset:4096
	v_pk_fma_f32 v[28:29], v[28:29], s[20:21], v[40:41] op_sel_hi:[1,0,1]
	v_pk_fma_f32 v[20:21], v[20:21], s[20:21], v[54:55] op_sel_hi:[1,0,1]
	v_add_f32_e32 v38, v28, v29
	v_add_f32_e32 v38, v38, v106
	v_pk_fma_f32 v[22:23], v[22:23], s[20:21], v[94:95] op_sel_hi:[1,0,1]
	v_add_f32_e32 v54, v20, v21
	v_pk_fma_f32 v[24:25], v[24:25], s[20:21], v[96:97] op_sel_hi:[1,0,1]
	v_add_f32_e32 v38, v107, v38
	v_add_f32_e32 v54, v54, v22
	v_pk_fma_f32 v[26:27], v[26:27], s[20:21], v[100:101] op_sel_hi:[1,0,1]
	v_add_f32_e32 v55, v24, v25
	v_add_f32_e32 v98, 0, v38
	v_add_f32_e32 v54, v23, v54
	v_add_f32_e32 v55, v55, v26
	v_add_f32_e32 v54, v98, v54
	v_add_f32_e32 v55, v27, v55
	v_pk_fma_f32 v[16:17], v[16:17], s[20:21], v[102:103] op_sel_hi:[1,0,1]
	v_add_f32_e32 v54, v54, v55
	v_pk_fma_f32 v[18:19], v[18:19], s[20:21], v[104:105] op_sel_hi:[1,0,1]
	v_add_f32_e32 v55, v16, v17
	v_add_f32_e32 v55, v55, v18
	v_add_f32_e32 v55, v19, v55
	v_add_f32_e32 v54, v54, v55
	ds_read_b128 v[38:41], v60
	ds_read_b128 v[42:45], v60 offset:4096
	ds_read_b128 v[46:49], v60 offset:8192
	ds_read_b128 v[50:53], v60 offset:12288
	ds_read_b128 v[108:111], v60 offset:16384
	ds_read_b128 v[122:125], v60 offset:20480
	ds_read_b128 v[130:133], v60 offset:24576
	ds_read_b128 v[134:137], v60 offset:28672
	ds_read_b128 v[138:141], v60 offset:32768
	ds_read_b128 v[142:145], v60 offset:36864
	ds_read_b128 v[146:149], v60 offset:40960
	ds_read_b128 v[150:153], v60 offset:45056
	ds_read_b128 v[154:157], v60 offset:49152
	v_add_f32_dpp v54, v54, v54 quad_perm:[1,0,3,2] row_mask:0xf bank_mask:0xf bound_ctrl:1
	s_nop 1
	v_add_f32_dpp v54, v54, v54 quad_perm:[2,3,0,1] row_mask:0xf bank_mask:0xf bound_ctrl:1
	s_nop 1
	v_add_f32_dpp v54, v54, v54 row_half_mirror row_mask:0xf bank_mask:0xf bound_ctrl:1
	s_nop 1
	v_add_f32_dpp v54, v54, v54 row_mirror row_mask:0xf bank_mask:0xf bound_ctrl:1
	s_nop 0
	v_readlane_b32 s2, v54, 16
	v_readlane_b32 s10, v54, 48
	v_readlane_b32 s0, v54, 0
	v_readlane_b32 s1, v54, 32
	v_mov_b32_e32 v54, s2
	v_mov_b32_e32 v55, s10
	v_pk_add_f32 v[54:55], s[0:1], v[54:55]
	s_nop 0
	v_add_f32_e32 v54, v54, v55
	v_mul_f32_e32 v54, 0x3a800000, v54
	v_pk_add_f32 v[28:29], v[28:29], v[54:55] op_sel_hi:[1,0] neg_lo:[0,1] neg_hi:[0,1]
	v_pk_add_f32 v[126:127], v[106:107], v[54:55] op_sel_hi:[1,0] neg_lo:[0,1] neg_hi:[0,1]
	v_pk_mul_f32 v[104:105], v[28:29], v[28:29]
	v_pk_mul_f32 v[106:107], v[126:127], v[126:127]
	v_pk_add_f32 v[158:159], v[20:21], v[54:55] op_sel_hi:[1,0] neg_lo:[0,1] neg_hi:[0,1]
	v_pk_add_f32 v[160:161], v[22:23], v[54:55] op_sel_hi:[1,0] neg_lo:[0,1] neg_hi:[0,1]
	v_pk_add_f32 v[100:101], v[24:25], v[54:55] op_sel_hi:[1,0] neg_lo:[0,1] neg_hi:[0,1]
	v_pk_add_f32 v[102:103], v[26:27], v[54:55] op_sel_hi:[1,0] neg_lo:[0,1] neg_hi:[0,1]
	v_pk_add_f32 v[94:95], v[16:17], v[54:55] op_sel_hi:[1,0] neg_lo:[0,1] neg_hi:[0,1]
	v_pk_add_f32 v[96:97], v[18:19], v[54:55] op_sel_hi:[1,0] neg_lo:[0,1] neg_hi:[0,1]
	v_add_f32_e32 v54, v104, v105
	v_add_f32_e32 v54, v106, v54
	v_pk_mul_f32 v[20:21], v[158:159], v[158:159]
	v_add_f32_e32 v54, v107, v54
	v_add_f32_e32 v20, v20, v54
	v_pk_mul_f32 v[22:23], v[160:161], v[160:161]
	v_add_f32_e32 v20, v21, v20
	v_add_f32_e32 v20, v22, v20
	v_pk_mul_f32 v[24:25], v[100:101], v[100:101]
	v_add_f32_e32 v20, v23, v20
	v_add_f32_e32 v20, v24, v20
	v_pk_mul_f32 v[26:27], v[102:103], v[102:103]
	v_add_f32_e32 v20, v25, v20
	v_add_f32_e32 v20, v26, v20
	v_pk_mul_f32 v[16:17], v[94:95], v[94:95]
	v_add_f32_e32 v20, v27, v20
	v_add_f32_e32 v16, v16, v20
	v_pk_mul_f32 v[18:19], v[96:97], v[96:97]
	v_add_f32_e32 v16, v17, v16
	v_add_f32_e32 v16, v18, v16
	v_add_f32_e32 v16, v19, v16
	s_nop 1
	v_add_f32_dpp v16, v16, v16 quad_perm:[1,0,3,2] row_mask:0xf bank_mask:0xf bound_ctrl:1
	s_nop 1
	v_add_f32_dpp v16, v16, v16 quad_perm:[2,3,0,1] row_mask:0xf bank_mask:0xf bound_ctrl:1
	s_nop 1
	v_add_f32_dpp v16, v16, v16 row_half_mirror row_mask:0xf bank_mask:0xf bound_ctrl:1
	s_nop 1
	v_add_f32_dpp v16, v16, v16 row_mirror row_mask:0xf bank_mask:0xf bound_ctrl:1
	s_nop 0
	v_readlane_b32 s2, v16, 16
	v_readlane_b32 s10, v16, 48
	v_readlane_b32 s0, v16, 0
	v_readlane_b32 s1, v16, 32
	v_mov_b32_e32 v16, s2
	v_mov_b32_e32 v17, s10
	v_pk_add_f32 v[16:17], s[0:1], v[16:17]
	s_mov_b32 s0, 0x800000
	v_add_f32_e32 v16, v16, v17
	v_fmamk_f32 v16, v16, 0x3a800000, v116
	v_cmp_gt_f32_e32 vcc, s0, v16
	v_mul_f32_e32 v17, 0x4b800000, v16
	s_nop 0
	v_cndmask_b32_e32 v16, v16, v17, vcc
	v_rsq_f32_e32 v54, v16
	ds_read_b128 v[16:19], v60 offset:53248
	s_waitcnt lgkmcnt(15)
	ds_read_b128 v[20:23], v60 offset:57344
	s_waitcnt lgkmcnt(15)
	ds_read_b128 v[24:27], v60 offset:61440
	s_waitcnt lgkmcnt(15)
	v_mul_f32_e32 v55, 0x45800000, v54
	v_cndmask_b32_e32 v98, v54, v55, vcc
	v_pk_mul_f32 v[28:29], v[28:29], v[98:99] op_sel_hi:[1,0]
	v_pk_fma_f32 v[106:107], v[30:31], v[28:29], v[34:35]
	v_pk_mul_f32 v[28:29], v[126:127], v[98:99] op_sel_hi:[1,0]
	s_waitcnt lgkmcnt(2)
	v_mul_f32_e32 v17, v107, v17
	v_pk_fma_f32 v[104:105], v[32:33], v[28:29], v[36:37]
	v_cvt_pk_bf16_f32 v28, v106, v107
	v_cvt_pk_bf16_f32 v29, v104, v105
	global_store_dwordx2 v[86:87], v[28:29], off offset:-1024
	v_mul_f32_e32 v28, v39, v107
	v_fmac_f32_e32 v28, v38, v106
	ds_read_b128 v[32:35], v234 offset:1024
	ds_read_b128 v[36:39], v234 offset:5120
	v_fmac_f32_e32 v28, v104, v40
	v_fmac_f32_e32 v28, v105, v41
	v_add_f32_e32 v54, 0, v28
	v_mul_f32_e32 v28, v107, v43
	v_fmac_f32_e32 v28, v106, v42
	v_fmac_f32_e32 v28, v104, v44
	v_fmac_f32_e32 v28, v105, v45
	v_add_f32_e32 v55, 0, v28
	v_mul_f32_e32 v28, v107, v47
	v_fmac_f32_e32 v28, v106, v46
	v_fmac_f32_e32 v28, v104, v48
	v_fmac_f32_e32 v28, v105, v49
	v_add_f32_e32 v46, 0, v28
	v_mul_f32_e32 v28, v107, v51
	v_fmac_f32_e32 v28, v106, v50
	v_fmac_f32_e32 v28, v104, v52
	v_fmac_f32_e32 v28, v105, v53
	v_add_f32_e32 v45, 0, v28
	v_mul_f32_e32 v28, v107, v109
	v_fmac_f32_e32 v28, v106, v108
	v_fmac_f32_e32 v28, v104, v110
	v_fmac_f32_e32 v28, v105, v111
	v_add_f32_e32 v44, 0, v28
	v_mul_f32_e32 v28, v107, v123
	v_fmac_f32_e32 v28, v106, v122
	v_fmac_f32_e32 v28, v104, v124
	v_fmac_f32_e32 v28, v105, v125
	v_add_f32_e32 v53, 0, v28
	v_mul_f32_e32 v28, v107, v131
	v_fmac_f32_e32 v28, v106, v130
	v_fmac_f32_e32 v28, v104, v132
	v_fmac_f32_e32 v28, v105, v133
	v_add_f32_e32 v52, 0, v28
	v_mul_f32_e32 v28, v107, v135
	v_fmac_f32_e32 v28, v106, v134
	v_fmac_f32_e32 v28, v104, v136
	v_fmac_f32_e32 v28, v105, v137
	v_add_f32_e32 v51, 0, v28
	v_mul_f32_e32 v28, v107, v139
	v_fmac_f32_e32 v28, v106, v138
	v_fmac_f32_e32 v28, v104, v140
	v_fmac_f32_e32 v28, v105, v141
	v_add_f32_e32 v50, 0, v28
	v_mul_f32_e32 v28, v107, v143
	v_fmac_f32_e32 v28, v106, v142
	v_fmac_f32_e32 v28, v104, v144
	v_fmac_f32_e32 v28, v105, v145
	v_add_f32_e32 v49, 0, v28
	v_mul_f32_e32 v28, v107, v147
	v_fmac_f32_e32 v28, v106, v146
	v_fmac_f32_e32 v28, v104, v148
	v_fmac_f32_e32 v28, v105, v149
	v_add_f32_e32 v48, 0, v28
	v_mul_f32_e32 v28, v107, v151
	v_fmac_f32_e32 v17, v106, v16
	s_waitcnt lgkmcnt(3)
	v_mul_f32_e32 v16, v107, v21
	v_fmac_f32_e32 v28, v106, v150
	v_fmac_f32_e32 v16, v106, v20
	v_fmac_f32_e32 v28, v104, v152
	v_fmac_f32_e32 v16, v104, v22
	v_fmac_f32_e32 v28, v105, v153
	v_fmac_f32_e32 v16, v105, v23
	v_add_f32_e32 v131, 0, v28
	v_mul_f32_e32 v28, v107, v155
	v_add_f32_e32 v122, 0, v16
	s_waitcnt lgkmcnt(2)
	v_mul_f32_e32 v16, v107, v25
	v_fmac_f32_e32 v28, v106, v154
	v_fmac_f32_e32 v16, v106, v24
	v_fmac_f32_e32 v28, v104, v156
	v_fmac_f32_e32 v17, v104, v18
	v_fmac_f32_e32 v16, v104, v26
	v_fmac_f32_e32 v28, v105, v157
	v_fmac_f32_e32 v17, v105, v19
	v_fmac_f32_e32 v16, v105, v27
	v_pk_mul_f32 v[40:41], v[158:159], v[98:99] op_sel_hi:[1,0]
	v_add_f32_e32 v125, 0, v28
	v_add_f32_e32 v124, 0, v17
	v_add_f32_e32 v123, 0, v16
	s_waitcnt lgkmcnt(0)
	v_pk_fma_f32 v[108:109], v[40:41], v[32:33], v[36:37]
	ds_read_b128 v[40:43], v60 offset:1024
	ds_read_b128 v[134:137], v60 offset:21504
	v_pk_mul_f32 v[32:33], v[160:161], v[98:99] op_sel_hi:[1,0]
	ds_read_b128 v[142:145], v60 offset:29696
	v_pk_fma_f32 v[110:111], v[32:33], v[34:35], v[38:39]
	s_waitcnt lgkmcnt(2)
	v_mul_f32_e32 v36, v109, v41
	v_cvt_pk_bf16_f32 v32, v108, v109
	v_cvt_pk_bf16_f32 v33, v110, v111
	v_fmac_f32_e32 v36, v108, v40
	global_store_dwordx2 v[86:87], v[32:33], off offset:-512
	ds_read_b128 v[32:35], v60 offset:5120
	v_fmac_f32_e32 v36, v110, v42
	v_fmac_f32_e32 v36, v111, v43
	v_add_f32_e32 v126, v54, v36
	s_waitcnt lgkmcnt(2)
	v_mul_f32_e32 v54, v109, v135
	s_waitcnt lgkmcnt(1)
	v_mul_f32_e32 v135, v109, v143
	v_fmac_f32_e32 v135, v108, v142
	v_fmac_f32_e32 v135, v110, v144
	v_fmac_f32_e32 v135, v111, v145
	ds_read_b128 v[144:147], v60 offset:50176
	s_waitcnt lgkmcnt(1)
	v_mul_f32_e32 v33, v109, v33
	v_fmac_f32_e32 v33, v108, v32
	v_fmac_f32_e32 v33, v110, v34
	v_fmac_f32_e32 v33, v111, v35
	ds_read_b128 v[36:39], v60 offset:9216
	v_add_f32_e32 v127, v55, v33
	ds_read_b128 v[32:35], v60 offset:13312
	ds_read_b128 v[40:43], v60 offset:17408
	ds_read_b128 v[138:141], v60 offset:25600
	v_fmac_f32_e32 v54, v108, v134
	v_fmac_f32_e32 v54, v110, v136
	s_waitcnt lgkmcnt(3)
	v_mul_f32_e32 v37, v109, v37
	s_waitcnt lgkmcnt(2)
	v_mul_f32_e32 v33, v109, v33
	v_fmac_f32_e32 v54, v111, v137
	v_fmac_f32_e32 v37, v108, v36
	v_fmac_f32_e32 v33, v108, v32
	v_add_f32_e32 v133, v53, v54
	s_waitcnt lgkmcnt(0)
	v_mul_f32_e32 v53, v109, v139
	v_fmac_f32_e32 v37, v110, v38
	v_fmac_f32_e32 v33, v110, v34
	v_mul_f32_e32 v41, v109, v41
	v_fmac_f32_e32 v53, v108, v138
	v_fmac_f32_e32 v37, v111, v39
	v_fmac_f32_e32 v33, v111, v35
	v_fmac_f32_e32 v41, v108, v40
	v_fmac_f32_e32 v53, v110, v140
	v_add_f32_e32 v129, v46, v37
	v_add_f32_e32 v130, v45, v33
	v_fmac_f32_e32 v41, v110, v42
	v_fmac_f32_e32 v53, v111, v141
	v_fmac_f32_e32 v41, v111, v43
	v_add_f32_e32 v134, v52, v53
	ds_read_b128 v[52:55], v60 offset:33792
	ds_read_b128 v[138:141], v60 offset:37888
	v_add_f32_e32 v132, v44, v41
	v_add_f32_e32 v135, v51, v135
	s_waitcnt lgkmcnt(1)
	v_mul_f32_e32 v51, v109, v53
	v_fmac_f32_e32 v51, v108, v52
	v_fmac_f32_e32 v51, v110, v54
	v_fmac_f32_e32 v51, v111, v55
	v_add_f32_e32 v136, v50, v51
	ds_read_b128 v[50:53], v60 offset:41984
	s_waitcnt lgkmcnt(1)
	v_mul_f32_e32 v54, v109, v139
	v_fmac_f32_e32 v54, v108, v138
	v_fmac_f32_e32 v54, v110, v140
	v_fmac_f32_e32 v54, v111, v141
	v_add_f32_e32 v137, v49, v54
	ds_read_b128 v[140:143], v60 offset:46080
	s_waitcnt lgkmcnt(1)
	v_mul_f32_e32 v49, v109, v51
	v_fmac_f32_e32 v49, v108, v50
	v_fmac_f32_e32 v49, v110, v52
	v_fmac_f32_e32 v49, v111, v53
	v_add_f32_e32 v138, v48, v49
	ds_read_b128 v[48:51], v234 offset:2048
	ds_read_b128 v[52:55], v234 offset:6144
	s_waitcnt lgkmcnt(2)
	v_mul_f32_e32 v139, v109, v141
	v_fmac_f32_e32 v139, v108, v140
	v_fmac_f32_e32 v139, v110, v142
	v_fmac_f32_e32 v139, v111, v143
	ds_read_b128 v[140:143], v60 offset:54272
	v_add_f32_e32 v131, v131, v139
	v_mul_f32_e32 v139, v109, v145
	v_fmac_f32_e32 v139, v108, v144
	v_fmac_f32_e32 v139, v110, v146
	v_fmac_f32_e32 v139, v111, v147
	ds_read_b128 v[144:147], v60 offset:58368
	v_add_f32_e32 v139, v125, v139
	s_waitcnt lgkmcnt(1)
	v_mul_f32_e32 v125, v109, v141
	v_fmac_f32_e32 v125, v108, v140
	v_fmac_f32_e32 v125, v110, v142
	v_fmac_f32_e32 v125, v111, v143
	ds_read_b128 v[140:143], v60 offset:62464
	v_add_f32_e32 v148, v124, v125
	s_waitcnt lgkmcnt(1)
	v_mul_f32_e32 v124, v109, v145
	v_fmac_f32_e32 v124, v108, v144
	v_fmac_f32_e32 v124, v110, v146
	v_fmac_f32_e32 v124, v111, v147
	v_add_f32_e32 v144, v122, v124
	s_waitcnt lgkmcnt(0)
	v_mul_f32_e32 v122, v109, v141
	v_fmac_f32_e32 v122, v108, v140
	v_fmac_f32_e32 v122, v110, v142
	v_fmac_f32_e32 v122, v111, v143
	v_add_f32_e32 v142, v123, v122
	v_mov_b32_e32 v122, v106
	v_mov_b32_e32 v123, v108
	v_mov_b32_e32 v108, v107
	v_mov_b32_e32 v106, v186
	v_mov_b32_e32 v124, v182
	v_mov_b32_e32 v140, v190
	v_mov_b32_e32 v125, v198
	v_mov_b32_e32 v107, v202
	v_pk_mul_f32 v[106:107], v[108:109], v[106:107]
	v_mov_b32_e32 v36, v187
	v_pk_fma_f32 v[106:107], v[122:123], v[124:125], v[106:107]
	v_mov_b32_e32 v124, v104
	v_mov_b32_e32 v125, v110
	v_mov_b32_e32 v110, v105
	v_mov_b32_e32 v104, v194
	v_mov_b32_e32 v141, v206
	v_pk_fma_f32 v[106:107], v[124:125], v[140:141], v[106:107]
	v_mov_b32_e32 v105, v210
	v_mov_b32_e32 v32, v183
	v_mov_b32_e32 v37, v203
	v_pk_mul_f32 v[24:25], v[108:109], v[36:37]
	v_pk_fma_f32 v[104:105], v[110:111], v[104:105], v[106:107]
	v_mov_b32_e32 v33, v199
	v_pk_fma_f32 v[24:25], v[122:123], v[32:33], v[24:25]
	v_mov_b32_e32 v40, v191
	v_add_f32_e32 v16, 0, v104
	v_mov_b32_e32 v41, v207
	v_pk_fma_f32 v[20:21], v[124:125], v[40:41], v[24:25]
	v_mov_b32_e32 v44, v195
	v_add_f32_e32 v107, v16, v105
	v_mov_b32_e32 v45, v211
	v_pk_fma_f32 v[16:17], v[110:111], v[44:45], v[20:21]
	v_mov_b32_e32 v20, v188
	v_add_f32_e32 v16, 0, v16
	v_mov_b32_e32 v21, v204
	v_add_f32_e32 v105, v16, v17
	v_mov_b32_e32 v16, v184
	v_mov_b32_e32 v17, v200
	v_pk_mul_f32 v[20:21], v[108:109], v[20:21]
	v_mov_b32_e32 v38, v189
	v_pk_fma_f32 v[16:17], v[122:123], v[16:17], v[20:21]
	v_mov_b32_e32 v20, v192
	v_mov_b32_e32 v21, v208
	v_pk_fma_f32 v[16:17], v[124:125], v[20:21], v[16:17]
	v_mov_b32_e32 v20, v196
	v_mov_b32_e32 v21, v212
	v_pk_fma_f32 v[16:17], v[110:111], v[20:21], v[16:17]
	v_mov_b32_e32 v34, v185
	v_add_f32_e32 v16, 0, v16
	v_add_f32_e32 v106, v16, v17
	v_mov_b32_e32 v39, v205
	v_pk_mul_f32 v[16:17], v[108:109], v[38:39]
	v_mov_b32_e32 v42, v193
	v_mov_b32_e32 v35, v201
	v_pk_fma_f32 v[16:17], v[122:123], v[34:35], v[16:17]
	v_mov_b32_e32 v46, v197
	v_mov_b32_e32 v43, v209
	v_pk_fma_f32 v[16:17], v[124:125], v[42:43], v[16:17]
	v_pk_mul_f32 v[20:21], v[102:103], v[98:99] op_sel_hi:[1,0]
	v_mov_b32_e32 v47, v213
	v_pk_fma_f32 v[16:17], v[110:111], v[46:47], v[16:17]
	v_pk_fma_f32 v[50:51], v[20:21], v[50:51], v[54:55]
	v_add_f32_e32 v16, 0, v16
	v_add_f32_e32 v104, v16, v17
	v_pk_mul_f32 v[16:17], v[100:101], v[98:99] op_sel_hi:[1,0]
	v_cvt_pk_bf16_f32 v21, v50, v51
	v_pk_fma_f32 v[48:49], v[16:17], v[48:49], v[52:53]
	ds_read_b128 v[16:19], v60 offset:2048
	v_cvt_pk_bf16_f32 v20, v48, v49
	global_store_dwordx2 v[86:87], v[20:21], off
	ds_read_b128 v[20:23], v60 offset:6144
	v_pk_mul_f32 v[46:47], v[94:95], v[98:99] op_sel_hi:[1,0]
	s_waitcnt lgkmcnt(1)
	v_mul_f32_e32 v17, v49, v17
	v_fmac_f32_e32 v17, v48, v16
	v_fmac_f32_e32 v17, v50, v18
	v_fmac_f32_e32 v17, v51, v19
	v_add_f32_e32 v42, v126, v17
	ds_read_b128 v[16:19], v60 offset:10240
	s_waitcnt lgkmcnt(1)
	v_mul_f32_e32 v21, v49, v21
	v_fmac_f32_e32 v21, v48, v20
	v_fmac_f32_e32 v21, v50, v22
	v_fmac_f32_e32 v21, v51, v23
	v_add_f32_e32 v41, v127, v21
	ds_read_b128 v[20:23], v60 offset:14336
	s_waitcnt lgkmcnt(1)
	v_mul_f32_e32 v17, v49, v17
	v_fmac_f32_e32 v17, v48, v16
	v_fmac_f32_e32 v17, v50, v18
	v_fmac_f32_e32 v17, v51, v19
	v_add_f32_e32 v40, v129, v17
	ds_read_b128 v[16:19], v60 offset:18432
	ds_read_b128 v[32:35], v234 offset:3072
	ds_read_b128 v[36:39], v234 offset:7168
	s_waitcnt lgkmcnt(3)
	v_mul_f32_e32 v21, v49, v21
	v_fmac_f32_e32 v21, v48, v20
	v_fmac_f32_e32 v21, v50, v22
	v_fmac_f32_e32 v21, v51, v23
	v_add_f32_e32 v45, v130, v21
	ds_read_b128 v[20:23], v60 offset:22528
	s_waitcnt lgkmcnt(3)
	v_mul_f32_e32 v17, v49, v17
	v_fmac_f32_e32 v17, v48, v16
	v_fmac_f32_e32 v17, v50, v18
	v_fmac_f32_e32 v17, v51, v19
	v_add_f32_e32 v44, v132, v17
	ds_read_b128 v[16:19], v60 offset:26624
	s_waitcnt lgkmcnt(1)
	v_mul_f32_e32 v21, v49, v21
	v_fmac_f32_e32 v21, v48, v20
	v_fmac_f32_e32 v21, v50, v22
	v_fmac_f32_e32 v21, v51, v23
	v_add_f32_e32 v124, v133, v21
	ds_read_b128 v[20:23], v60 offset:30720
	s_waitcnt lgkmcnt(1)
	v_mul_f32_e32 v17, v49, v17
	v_fmac_f32_e32 v17, v48, v16
	v_fmac_f32_e32 v17, v50, v18
	v_fmac_f32_e32 v17, v51, v19
	s_waitcnt lgkmcnt(0)
	v_mul_f32_e32 v21, v49, v21
	v_fmac_f32_e32 v21, v48, v20
	v_fmac_f32_e32 v21, v50, v22
	v_add_f32_e32 v123, v134, v17
	ds_read_b128 v[16:19], v60 offset:34816
	v_fmac_f32_e32 v21, v51, v23
	v_add_f32_e32 v122, v135, v21
	ds_read_b128 v[20:23], v60 offset:38912
	s_waitcnt lgkmcnt(1)
	v_mul_f32_e32 v17, v49, v17
	v_fmac_f32_e32 v17, v48, v16
	v_fmac_f32_e32 v17, v50, v18
	s_waitcnt lgkmcnt(0)
	v_mul_f32_e32 v21, v49, v21
	v_fmac_f32_e32 v21, v48, v20
	v_fmac_f32_e32 v17, v51, v19
	v_fmac_f32_e32 v21, v50, v22
	v_add_f32_e32 v111, v136, v17
	ds_read_b128 v[16:19], v60 offset:43008
	v_fmac_f32_e32 v21, v51, v23
	v_add_f32_e32 v110, v137, v21
	ds_read_b128 v[20:23], v60 offset:47104
	s_waitcnt lgkmcnt(1)
	v_mul_f32_e32 v17, v49, v17
	v_fmac_f32_e32 v17, v48, v16
	v_fmac_f32_e32 v17, v50, v18
	s_waitcnt lgkmcnt(0)
	v_mul_f32_e32 v21, v49, v21
	v_fmac_f32_e32 v21, v48, v20
	v_fmac_f32_e32 v17, v51, v19
	v_fmac_f32_e32 v21, v50, v22
	v_add_f32_e32 v109, v138, v17
	ds_read_b128 v[16:19], v60 offset:51200
	v_fmac_f32_e32 v21, v51, v23
	v_add_f32_e32 v108, v131, v21
	ds_read_b128 v[20:23], v60 offset:55296
	s_waitcnt lgkmcnt(1)
	v_mul_f32_e32 v17, v49, v17
	v_fmac_f32_e32 v17, v48, v16
	v_fmac_f32_e32 v17, v50, v18
	s_waitcnt lgkmcnt(0)
	v_mul_f32_e32 v21, v49, v21
	v_fmac_f32_e32 v21, v48, v20
	v_fmac_f32_e32 v17, v51, v19
	v_fmac_f32_e32 v21, v50, v22
	v_add_f32_e32 v103, v139, v17
	ds_read_b128 v[16:19], v60 offset:59392
	v_fmac_f32_e32 v21, v51, v23
	v_add_f32_e32 v102, v148, v21
	ds_read_b128 v[20:23], v60 offset:63488
	s_waitcnt lgkmcnt(1)
	v_mul_f32_e32 v17, v49, v17
	v_fmac_f32_e32 v17, v48, v16
	v_fmac_f32_e32 v17, v50, v18
	s_waitcnt lgkmcnt(0)
	v_mul_f32_e32 v16, v49, v21
	v_fmac_f32_e32 v16, v48, v20
	v_fmac_f32_e32 v16, v50, v22
	v_fmac_f32_e32 v17, v51, v19
	v_fmac_f32_e32 v16, v51, v23
	v_add_f32_e32 v100, v144, v17
	v_add_f32_e32 v101, v142, v16
	v_pk_fma_f32 v[52:53], v[46:47], v[32:33], v[36:37]
	v_pk_mul_f32 v[32:33], v[96:97], v[98:99] op_sel_hi:[1,0]
	ds_read_b128 v[94:97], v60 offset:3072
	v_pk_fma_f32 v[54:55], v[32:33], v[34:35], v[38:39]
	v_cvt_pk_bf16_f32 v32, v52, v53
	v_cvt_pk_bf16_f32 v33, v54, v55
	global_store_dwordx2 v[86:87], v[32:33], off offset:512
	ds_read_b128 v[32:35], v60 offset:7168
	s_waitcnt lgkmcnt(1)
	v_mul_f32_e32 v36, v53, v95
	v_fmac_f32_e32 v36, v52, v94
	v_fmac_f32_e32 v36, v54, v96
	v_fmac_f32_e32 v36, v55, v97
	v_add_f32_e32 v94, v42, v36
	ds_read_b128 v[36:39], v60 offset:11264
	ds_read_b128 v[130:133], v60 offset:15360
	s_waitcnt lgkmcnt(2)
	v_mul_f32_e32 v33, v53, v33
	v_fmac_f32_e32 v33, v52, v32
	v_fmac_f32_e32 v33, v54, v34
	s_waitcnt lgkmcnt(1)
	v_mul_f32_e32 v32, v53, v37
	v_fmac_f32_e32 v32, v52, v36
	v_fmac_f32_e32 v32, v54, v38
	v_fmac_f32_e32 v33, v55, v35
	v_fmac_f32_e32 v32, v55, v39
	v_add_f32_e32 v95, v41, v33
	v_add_f32_e32 v96, v40, v32
	ds_read_b128 v[40:43], v60 offset:19456
	s_waitcnt lgkmcnt(1)
	v_mul_f32_e32 v36, v53, v131
	v_fmac_f32_e32 v36, v52, v130
	v_fmac_f32_e32 v36, v54, v132
	v_fmac_f32_e32 v36, v55, v133
	v_add_f32_e32 v97, v45, v36
	ds_read_b128 v[130:133], v60 offset:23552
	s_waitcnt lgkmcnt(1)
	v_mul_f32_e32 v45, v53, v41
	v_fmac_f32_e32 v45, v52, v40
	v_fmac_f32_e32 v45, v54, v42
	v_fmac_f32_e32 v45, v55, v43
	v_add_f32_e32 v125, v44, v45
	ds_read_b128 v[134:137], v60 offset:27648
	s_waitcnt lgkmcnt(1)
	v_mul_f32_e32 v98, v53, v131
	v_fmac_f32_e32 v98, v52, v130
	v_fmac_f32_e32 v98, v54, v132
	v_fmac_f32_e32 v98, v55, v133
	ds_read_b128 v[130:133], v60 offset:31744
	v_add_f32_e32 v124, v124, v98
	s_waitcnt lgkmcnt(1)
	v_mul_f32_e32 v98, v53, v135
	v_fmac_f32_e32 v98, v52, v134
	v_fmac_f32_e32 v98, v54, v136
	v_fmac_f32_e32 v98, v55, v137
	ds_read_b128 v[134:137], v60 offset:35840
	v_add_f32_e32 v98, v123, v98
	s_waitcnt lgkmcnt(1)
	v_mul_f32_e32 v123, v53, v131
	v_fmac_f32_e32 v123, v52, v130
	v_fmac_f32_e32 v123, v54, v132
	v_fmac_f32_e32 v123, v55, v133
	ds_read_b128 v[130:133], v60 offset:39936
	v_add_f32_e32 v122, v122, v123
	s_waitcnt lgkmcnt(1)
	v_mul_f32_e32 v123, v53, v135
	v_fmac_f32_e32 v123, v52, v134
	v_fmac_f32_e32 v123, v54, v136
	v_fmac_f32_e32 v123, v55, v137
	ds_read_b128 v[134:137], v60 offset:44032
	v_add_f32_e32 v111, v111, v123
	s_waitcnt lgkmcnt(1)
	v_mul_f32_e32 v123, v53, v131
	v_fmac_f32_e32 v123, v52, v130
	v_fmac_f32_e32 v123, v54, v132
	v_fmac_f32_e32 v123, v55, v133
	ds_read_b128 v[130:133], v60 offset:48128
	v_add_f32_e32 v110, v110, v123
	s_waitcnt lgkmcnt(1)
	v_mul_f32_e32 v123, v53, v135
	v_fmac_f32_e32 v123, v52, v134
	v_fmac_f32_e32 v123, v54, v136
	v_fmac_f32_e32 v123, v55, v137
	ds_read_b128 v[134:137], v60 offset:52224
	v_add_f32_e32 v109, v109, v123
	s_waitcnt lgkmcnt(1)
	v_mul_f32_e32 v123, v53, v131
	v_fmac_f32_e32 v123, v52, v130
	v_fmac_f32_e32 v123, v54, v132
	v_fmac_f32_e32 v123, v55, v133
	ds_read_b128 v[130:133], v60 offset:56320
	v_add_f32_e32 v108, v108, v123
	s_waitcnt lgkmcnt(1)
	v_mul_f32_e32 v123, v53, v135
	v_fmac_f32_e32 v123, v52, v134
	v_fmac_f32_e32 v123, v54, v136
	v_fmac_f32_e32 v123, v55, v137
	ds_read_b128 v[134:137], v60 offset:60416
	v_add_f32_e32 v103, v103, v123
	s_waitcnt lgkmcnt(1)
	v_mul_f32_e32 v123, v53, v131
	v_fmac_f32_e32 v123, v52, v130
	v_fmac_f32_e32 v123, v54, v132
	v_fmac_f32_e32 v123, v55, v133
	ds_read_b128 v[130:133], v60 offset:64512
	v_add_f32_e32 v102, v102, v123
	s_waitcnt lgkmcnt(1)
	v_mul_f32_e32 v123, v53, v135
	v_fmac_f32_e32 v123, v52, v134
	v_fmac_f32_e32 v123, v54, v136
	v_fmac_f32_e32 v123, v55, v137
	v_add_f32_e32 v123, v100, v123
	s_waitcnt lgkmcnt(0)
	v_mul_f32_e32 v100, v53, v131
	v_fmac_f32_e32 v100, v52, v130
	v_fmac_f32_e32 v100, v54, v132
	v_fmac_f32_e32 v100, v55, v133
	v_add_f32_e32 v129, v101, v100
	v_mov_b32_e32 v100, v48
	v_mov_b32_e32 v101, v52
	v_mov_b32_e32 v52, v49
	v_mov_b32_e32 v48, v218
	v_mov_b32_e32 v126, v214
	v_mov_b32_e32 v130, v222
	v_mov_b32_e32 v127, v230
	v_mov_b32_e32 v49, v238
	v_pk_mul_f32 v[48:49], v[52:53], v[48:49]
	v_mov_b32_e32 v36, v219
	v_pk_fma_f32 v[48:49], v[100:101], v[126:127], v[48:49]
	v_mov_b32_e32 v126, v50
	v_mov_b32_e32 v127, v54
	v_mov_b32_e32 v131, v242
	v_pk_fma_f32 v[48:49], v[126:127], v[130:131], v[48:49]
	v_mov_b32_e32 v54, v51
	v_mov_b32_e32 v50, v226
	v_mov_b32_e32 v51, v246
	v_mov_b32_e32 v32, v215
	v_mov_b32_e32 v37, v239
	v_pk_mul_f32 v[24:25], v[52:53], v[36:37]
	v_pk_fma_f32 v[48:49], v[54:55], v[50:51], v[48:49]
	v_mov_b32_e32 v33, v231
	v_pk_fma_f32 v[24:25], v[100:101], v[32:33], v[24:25]
	v_mov_b32_e32 v40, v223
	v_add_f32_e32 v16, v107, v48
	v_mov_b32_e32 v41, v243
	v_pk_fma_f32 v[20:21], v[126:127], v[40:41], v[24:25]
	v_mov_b32_e32 v44, v227
	v_add_f32_e32 v28, v16, v49
	v_mov_b32_e32 v45, v247
	v_pk_fma_f32 v[16:17], v[54:55], v[44:45], v[20:21]
	v_mov_b32_e32 v20, v220
	v_add_f32_e32 v16, v105, v16
	v_mov_b32_e32 v21, v240
	v_add_f32_e32 v24, v16, v17
	v_mov_b32_e32 v16, v216
	v_mov_b32_e32 v17, v232
	v_pk_mul_f32 v[20:21], v[52:53], v[20:21]
	v_mov_b32_e32 v38, v221
	v_pk_fma_f32 v[16:17], v[100:101], v[16:17], v[20:21]
	v_mov_b32_e32 v20, v224
	v_mov_b32_e32 v21, v244
	v_pk_fma_f32 v[16:17], v[126:127], v[20:21], v[16:17]
	v_mov_b32_e32 v20, v228
	v_mov_b32_e32 v21, v248
	v_pk_fma_f32 v[16:17], v[54:55], v[20:21], v[16:17]
	v_mov_b32_e32 v34, v217
	v_add_f32_e32 v16, v106, v16
	v_add_f32_e32 v20, v16, v17
	v_mov_b32_e32 v39, v241
	v_pk_mul_f32 v[16:17], v[52:53], v[38:39]
	v_mov_b32_e32 v42, v225
	v_mov_b32_e32 v35, v233
	v_pk_fma_f32 v[16:17], v[100:101], v[34:35], v[16:17]
	v_mov_b32_e32 v46, v229
	v_mov_b32_e32 v43, v245
	v_pk_fma_f32 v[16:17], v[126:127], v[42:43], v[16:17]
	v_add_f32_dpp v18, v24, v24 quad_perm:[1,0,3,2] row_mask:0xf bank_mask:0xf bound_ctrl:1
	v_mov_b32_e32 v47, v249
	v_pk_fma_f32 v[16:17], v[54:55], v[46:47], v[16:17]
	v_add_f32_dpp v20, v20, v20 quad_perm:[1,0,3,2] row_mask:0xf bank_mask:0xf bound_ctrl:1
	v_add_f32_e32 v16, v104, v16
	v_add_f32_e32 v22, v16, v17
	v_add_f32_dpp v18, v18, v18 quad_perm:[2,3,0,1] row_mask:0xf bank_mask:0xf bound_ctrl:1
	v_add_f32_dpp v16, v28, v28 quad_perm:[1,0,3,2] row_mask:0xf bank_mask:0xf bound_ctrl:1
	v_add_f32_dpp v20, v20, v20 quad_perm:[2,3,0,1] row_mask:0xf bank_mask:0xf bound_ctrl:1
	v_add_f32_dpp v18, v18, v18 row_half_mirror row_mask:0xf bank_mask:0xf bound_ctrl:1
	v_add_f32_dpp v16, v16, v16 quad_perm:[2,3,0,1] row_mask:0xf bank_mask:0xf bound_ctrl:1
	v_add_f32_dpp v20, v20, v20 row_half_mirror row_mask:0xf bank_mask:0xf bound_ctrl:1
	v_add_f32_dpp v18, v18, v18 row_mirror row_mask:0xf bank_mask:0xf bound_ctrl:1
	v_add_f32_dpp v16, v16, v16 row_half_mirror row_mask:0xf bank_mask:0xf bound_ctrl:1
	v_add_f32_dpp v20, v20, v20 row_mirror row_mask:0xf bank_mask:0xf bound_ctrl:1
	s_nop 0
	v_add_f32_dpp v16, v16, v16 row_mirror row_mask:0xf bank_mask:0xf bound_ctrl:1
	s_nop 0
	v_readlane_b32 s2, v16, 16
	v_readlane_b32 s10, v16, 48
	v_readlane_b32 s0, v16, 0
	v_readlane_b32 s1, v16, 32
	v_mov_b32_e32 v16, s2
	v_mov_b32_e32 v17, s10
	v_readlane_b32 s2, v18, 16
	v_readlane_b32 s10, v18, 48
	v_pk_add_f32 v[16:17], s[0:1], v[16:17]
	v_readlane_b32 s0, v18, 0
	v_readlane_b32 s1, v18, 32
	v_mov_b32_e32 v18, s2
	v_mov_b32_e32 v19, s10
	v_readlane_b32 s2, v20, 16
	v_readlane_b32 s10, v20, 48
	v_pk_add_f32 v[18:19], s[0:1], v[18:19]
	v_readlane_b32 s0, v20, 0
	v_readlane_b32 s1, v20, 32
	v_mov_b32_e32 v20, s2
	v_mov_b32_e32 v21, s10
	v_pk_add_f32 v[20:21], s[0:1], v[20:21]
	v_mov_b32_e32 v25, v18
	v_add_f32_e32 v26, v20, v21
	v_add_f32_dpp v20, v22, v22 quad_perm:[1,0,3,2] row_mask:0xf bank_mask:0xf bound_ctrl:1
	v_mov_b32_e32 v18, v17
	s_nop 0
	v_add_f32_dpp v20, v20, v20 quad_perm:[2,3,0,1] row_mask:0xf bank_mask:0xf bound_ctrl:1
	s_nop 1
	v_add_f32_dpp v20, v20, v20 row_half_mirror row_mask:0xf bank_mask:0xf bound_ctrl:1
	s_nop 1
	v_add_f32_dpp v20, v20, v20 row_mirror row_mask:0xf bank_mask:0xf bound_ctrl:1
	s_nop 0
	v_readlane_b32 s2, v20, 16
	v_readlane_b32 s10, v20, 48
	v_readlane_b32 s0, v20, 0
	v_readlane_b32 s1, v20, 32
	v_mov_b32_e32 v20, s2
	v_mov_b32_e32 v21, s10
	v_pk_add_f32 v[20:21], s[0:1], v[20:21]
	s_nop 0
	v_add_f32_e32 v27, v20, v21
	v_add_f32_dpp v20, v94, v94 quad_perm:[1,0,3,2] row_mask:0xf bank_mask:0xf bound_ctrl:1
	s_nop 1
	v_add_f32_dpp v20, v20, v20 quad_perm:[2,3,0,1] row_mask:0xf bank_mask:0xf bound_ctrl:1
	s_nop 1
	v_add_f32_dpp v20, v20, v20 row_half_mirror row_mask:0xf bank_mask:0xf bound_ctrl:1
	s_nop 1
	v_add_f32_dpp v20, v20, v20 row_mirror row_mask:0xf bank_mask:0xf bound_ctrl:1
	s_nop 0
	v_readlane_b32 s14, v20, 0
	v_readlane_b32 s94, v20, 16
	v_readlane_b32 s15, v20, 32
	v_readlane_b32 s95, v20, 48
	v_add_f32_dpp v20, v95, v95 quad_perm:[1,0,3,2] row_mask:0xf bank_mask:0xf bound_ctrl:1
	s_nop 1
	v_add_f32_dpp v20, v20, v20 quad_perm:[2,3,0,1] row_mask:0xf bank_mask:0xf bound_ctrl:1
	s_nop 1
	v_add_f32_dpp v20, v20, v20 row_half_mirror row_mask:0xf bank_mask:0xf bound_ctrl:1
	s_nop 1
	v_add_f32_dpp v20, v20, v20 row_mirror row_mask:0xf bank_mask:0xf bound_ctrl:1
	s_nop 0
	v_readlane_b32 s87, v20, 0
	v_readlane_b32 s91, v20, 16
	v_readlane_b32 s90, v20, 32
	v_readlane_b32 s92, v20, 48
	v_add_f32_dpp v20, v96, v96 quad_perm:[1,0,3,2] row_mask:0xf bank_mask:0xf bound_ctrl:1
	s_nop 1
	v_add_f32_dpp v20, v20, v20 quad_perm:[2,3,0,1] row_mask:0xf bank_mask:0xf bound_ctrl:1
	s_nop 1
	v_add_f32_dpp v20, v20, v20 row_half_mirror row_mask:0xf bank_mask:0xf bound_ctrl:1
	s_nop 1
	v_add_f32_dpp v20, v20, v20 row_mirror row_mask:0xf bank_mask:0xf bound_ctrl:1
	s_nop 0
	v_readlane_b32 s65, v20, 0
	v_readlane_b32 s75, v20, 16
	v_readlane_b32 s66, v20, 32
	v_readlane_b32 s78, v20, 48
	v_add_f32_dpp v20, v97, v97 quad_perm:[1,0,3,2] row_mask:0xf bank_mask:0xf bound_ctrl:1
	s_nop 1
	v_add_f32_dpp v20, v20, v20 quad_perm:[2,3,0,1] row_mask:0xf bank_mask:0xf bound_ctrl:1
	s_nop 1
	v_add_f32_dpp v20, v20, v20 row_half_mirror row_mask:0xf bank_mask:0xf bound_ctrl:1
	s_nop 1
	v_add_f32_dpp v20, v20, v20 row_mirror row_mask:0xf bank_mask:0xf bound_ctrl:1
	s_nop 0
	v_readlane_b32 s51, v20, 0
	v_readlane_b32 s53, v20, 16
	v_readlane_b32 s52, v20, 32
	v_readlane_b32 s54, v20, 48
	v_add_f32_dpp v20, v125, v125 quad_perm:[1,0,3,2] row_mask:0xf bank_mask:0xf bound_ctrl:1
	s_nop 1
	v_add_f32_dpp v20, v20, v20 quad_perm:[2,3,0,1] row_mask:0xf bank_mask:0xf bound_ctrl:1
	s_nop 1
	v_add_f32_dpp v20, v20, v20 row_half_mirror row_mask:0xf bank_mask:0xf bound_ctrl:1
	s_nop 1
	v_add_f32_dpp v20, v20, v20 row_mirror row_mask:0xf bank_mask:0xf bound_ctrl:1
	s_nop 0
	v_readlane_b32 s35, v20, 0
	v_readlane_b32 s37, v20, 16
	v_readlane_b32 s36, v20, 32
	v_readlane_b32 s38, v20, 48
	v_add_f32_dpp v20, v124, v124 quad_perm:[1,0,3,2] row_mask:0xf bank_mask:0xf bound_ctrl:1
	s_nop 1
	v_add_f32_dpp v20, v20, v20 quad_perm:[2,3,0,1] row_mask:0xf bank_mask:0xf bound_ctrl:1
	s_nop 1
	v_add_f32_dpp v20, v20, v20 row_half_mirror row_mask:0xf bank_mask:0xf bound_ctrl:1
	s_nop 1
	v_add_f32_dpp v24, v20, v20 row_mirror row_mask:0xf bank_mask:0xf bound_ctrl:1
	s_nop 0
	v_readlane_b32 s23, v24, 0
	v_readlane_b32 s27, v24, 16
	v_readlane_b32 s26, v24, 32
	v_readlane_b32 s93, v24, 48
	v_add_f32_dpp v24, v98, v98 quad_perm:[1,0,3,2] row_mask:0xf bank_mask:0xf bound_ctrl:1
	s_nop 1
	v_add_f32_dpp v24, v24, v24 quad_perm:[2,3,0,1] row_mask:0xf bank_mask:0xf bound_ctrl:1
	s_nop 1
	v_add_f32_dpp v24, v24, v24 row_half_mirror row_mask:0xf bank_mask:0xf bound_ctrl:1
	s_nop 1
	v_add_f32_dpp v24, v24, v24 row_mirror row_mask:0xf bank_mask:0xf bound_ctrl:1
	s_nop 0
	v_readlane_b32 s81, v24, 0
	v_readlane_b32 s83, v24, 16
	v_readlane_b32 s82, v24, 32
	v_readlane_b32 s84, v24, 48
	v_add_f32_dpp v24, v122, v122 quad_perm:[1,0,3,2] row_mask:0xf bank_mask:0xf bound_ctrl:1
	s_nop 1
	v_add_f32_dpp v24, v24, v24 quad_perm:[2,3,0,1] row_mask:0xf bank_mask:0xf bound_ctrl:1
	s_nop 1
	v_add_f32_dpp v24, v24, v24 row_half_mirror row_mask:0xf bank_mask:0xf bound_ctrl:1
	s_nop 1
	v_add_f32_dpp v24, v24, v24 row_mirror row_mask:0xf bank_mask:0xf bound_ctrl:1
	s_nop 0
	v_readlane_b32 s63, v24, 0
	v_readlane_b32 s67, v24, 16
	v_readlane_b32 s64, v24, 32
	v_readlane_b32 s70, v24, 48
	v_add_f32_dpp v24, v111, v111 quad_perm:[1,0,3,2] row_mask:0xf bank_mask:0xf bound_ctrl:1
	s_nop 1
	v_add_f32_dpp v24, v24, v24 quad_perm:[2,3,0,1] row_mask:0xf bank_mask:0xf bound_ctrl:1
	s_nop 1
	v_add_f32_dpp v24, v24, v24 row_half_mirror row_mask:0xf bank_mask:0xf bound_ctrl:1
	s_nop 1
	v_add_f32_dpp v24, v24, v24 row_mirror row_mask:0xf bank_mask:0xf bound_ctrl:1
	s_nop 0
	v_readlane_b32 s59, v24, 0
	v_readlane_b32 s61, v24, 16
	v_readlane_b32 s60, v24, 32
	v_readlane_b32 s62, v24, 48
	v_add_f32_dpp v24, v110, v110 quad_perm:[1,0,3,2] row_mask:0xf bank_mask:0xf bound_ctrl:1
	s_nop 1
	v_add_f32_dpp v24, v24, v24 quad_perm:[2,3,0,1] row_mask:0xf bank_mask:0xf bound_ctrl:1
	s_nop 1
	v_add_f32_dpp v24, v24, v24 row_half_mirror row_mask:0xf bank_mask:0xf bound_ctrl:1
	s_nop 1
	v_add_f32_dpp v24, v24, v24 row_mirror row_mask:0xf bank_mask:0xf bound_ctrl:1
	s_nop 0
	v_readlane_b32 s55, v24, 0
	v_readlane_b32 s57, v24, 16
	v_readlane_b32 s56, v24, 32
	v_readlane_b32 s58, v24, 48
	v_add_f32_dpp v24, v109, v109 quad_perm:[1,0,3,2] row_mask:0xf bank_mask:0xf bound_ctrl:1
	s_nop 1
	v_add_f32_dpp v24, v24, v24 quad_perm:[2,3,0,1] row_mask:0xf bank_mask:0xf bound_ctrl:1
	s_nop 1
	v_add_f32_dpp v24, v24, v24 row_half_mirror row_mask:0xf bank_mask:0xf bound_ctrl:1
	s_nop 1
	v_add_f32_dpp v24, v24, v24 row_mirror row_mask:0xf bank_mask:0xf bound_ctrl:1
	s_nop 0
	v_readlane_b32 s47, v24, 0
	v_readlane_b32 s49, v24, 16
	v_readlane_b32 s48, v24, 32
	v_readlane_b32 s50, v24, 48
	v_add_f32_dpp v24, v108, v108 quad_perm:[1,0,3,2] row_mask:0xf bank_mask:0xf bound_ctrl:1
	s_nop 1
	v_add_f32_dpp v24, v24, v24 quad_perm:[2,3,0,1] row_mask:0xf bank_mask:0xf bound_ctrl:1
	s_nop 1
	v_add_f32_dpp v24, v24, v24 row_half_mirror row_mask:0xf bank_mask:0xf bound_ctrl:1
	s_nop 1
	v_add_f32_dpp v24, v24, v24 row_mirror row_mask:0xf bank_mask:0xf bound_ctrl:1
	s_nop 0
	v_readlane_b32 s43, v24, 0
	v_readlane_b32 s45, v24, 16
	v_readlane_b32 s44, v24, 32
	v_readlane_b32 s46, v24, 48
	v_add_f32_dpp v24, v103, v103 quad_perm:[1,0,3,2] row_mask:0xf bank_mask:0xf bound_ctrl:1
	s_nop 1
	v_add_f32_dpp v24, v24, v24 quad_perm:[2,3,0,1] row_mask:0xf bank_mask:0xf bound_ctrl:1
	s_nop 1
	v_add_f32_dpp v24, v24, v24 row_half_mirror row_mask:0xf bank_mask:0xf bound_ctrl:1
	s_nop 1
	v_add_f32_dpp v24, v24, v24 row_mirror row_mask:0xf bank_mask:0xf bound_ctrl:1
	s_nop 0
	v_readlane_b32 s39, v24, 0
	v_readlane_b32 s41, v24, 16
	v_readlane_b32 s40, v24, 32
	v_readlane_b32 s42, v24, 48
	v_add_f32_dpp v24, v102, v102 quad_perm:[1,0,3,2] row_mask:0xf bank_mask:0xf bound_ctrl:1
	s_nop 1
	v_add_f32_dpp v24, v24, v24 quad_perm:[2,3,0,1] row_mask:0xf bank_mask:0xf bound_ctrl:1
	s_nop 1
	v_add_f32_dpp v24, v24, v24 row_half_mirror row_mask:0xf bank_mask:0xf bound_ctrl:1
	s_nop 1
	v_add_f32_dpp v24, v24, v24 row_mirror row_mask:0xf bank_mask:0xf bound_ctrl:1
	s_nop 0
	v_readlane_b32 s30, v24, 0
	v_readlane_b32 s33, v24, 16
	v_readlane_b32 s31, v24, 32
	v_readlane_b32 s34, v24, 48
	v_add_f32_dpp v24, v123, v123 quad_perm:[1,0,3,2] row_mask:0xf bank_mask:0xf bound_ctrl:1
	s_nop 1
	v_add_f32_dpp v24, v24, v24 quad_perm:[2,3,0,1] row_mask:0xf bank_mask:0xf bound_ctrl:1
	s_nop 1
	v_add_f32_dpp v24, v24, v24 row_half_mirror row_mask:0xf bank_mask:0xf bound_ctrl:1
	s_nop 1
	v_add_f32_dpp v28, v24, v24 row_mirror row_mask:0xf bank_mask:0xf bound_ctrl:1
	v_add_f32_dpp v24, v129, v129 quad_perm:[1,0,3,2] row_mask:0xf bank_mask:0xf bound_ctrl:1
	v_readlane_b32 s28, v28, 0
	v_readlane_b32 s29, v28, 16
	v_add_f32_dpp v24, v24, v24 quad_perm:[2,3,0,1] row_mask:0xf bank_mask:0xf bound_ctrl:1
	v_readlane_b32 s85, v28, 32
	v_readlane_b32 s86, v28, 48
	v_add_f32_dpp v24, v24, v24 row_half_mirror row_mask:0xf bank_mask:0xf bound_ctrl:1
	s_nop 1
	v_add_f32_dpp v29, v24, v24 row_mirror row_mask:0xf bank_mask:0xf bound_ctrl:1
	v_mov_b32_e32 v24, v16
	v_pk_add_f32 v[16:17], v[24:25], v[18:19]
	v_mov_b32_e32 v20, v178
	v_mov_b32_e32 v21, v179
	v_mov_b32_e32 v22, v180
	v_mov_b32_e32 v23, v181
	v_add_f32_e32 v19, v26, v22
	v_pk_add_f32 v[16:17], v[16:17], v[20:21]
	v_add_f32_e32 v18, v27, v23
	v_cmp_gt_f32_e32 vcc, v17, v16
	v_mov_b32_e32 v22, 0
	v_readlane_b32 s71, v29, 0
	v_cndmask_b32_e32 v20, v16, v17, vcc
	v_cmp_gt_f32_e64 s[12:13], v19, v20
	v_cndmask_b32_e64 v21, 0, 1, vcc
	s_and_b64 s[10:11], s[12:13], exec
	v_cndmask_b32_e64 v20, v20, v19, s[12:13]
	v_cmp_ngt_f32_e64 s[0:1], v18, v20
	v_readfirstlane_b32 s2, v21
	s_cselect_b32 s2, 2, s2
	s_and_b64 s[10:11], s[0:1], exec
	s_cselect_b32 s2, s2, 3
	s_cmp_eq_u32 s2, 0
	s_cselect_b64 s[24:25], -1, 0
	s_cmp_lg_u32 s2, 0
	v_mov_b32_e32 v21, 0
	v_readlane_b32 s79, v29, 16
	v_readlane_b32 s74, v29, 32
	v_readlane_b32 s80, v29, 48
	v_cmp_gt_f32_e64 s[10:11], v18, v20
	s_waitcnt lgkmcnt(0)
	s_cbranch_scc0 .LBB0_1684
	v_cndmask_b32_e64 v23, 0, 1, s[24:25]
	v_cmp_ne_u32_e64 s[14:15], 1, v23
	s_andn2_b64 vcc, exec, s[24:25]
	s_cbranch_vccz .LBB0_1685

	.amdhsa_kernel _Z4mega6Params
		.amdhsa_group_segment_fixed_size 81920
		.amdhsa_private_segment_fixed_size 0
		.amdhsa_kernarg_size 488
		.amdhsa_user_sgpr_count 2
		.amdhsa_user_sgpr_dispatch_ptr 0
		.amdhsa_user_sgpr_queue_ptr 0
		.amdhsa_user_sgpr_kernarg_segment_ptr 1
		.amdhsa_user_sgpr_dispatch_id 0
		.amdhsa_user_sgpr_kernarg_preload_length 0
		.amdhsa_user_sgpr_kernarg_preload_offset 0
		.amdhsa_user_sgpr_private_segment_size 0
		.amdhsa_uses_dynamic_stack 0
		.amdhsa_enable_private_segment 0
		.amdhsa_system_sgpr_workgroup_id_x 1
		.amdhsa_system_sgpr_workgroup_id_y 0
		.amdhsa_system_sgpr_workgroup_id_z 0
		.amdhsa_system_sgpr_workgroup_info 0
		.amdhsa_system_vgpr_workitem_id 2
		.amdhsa_next_free_vgpr 256
		.amdhsa_next_free_sgpr 102
		.amdhsa_accum_offset 256
		.amdhsa_reserve_vcc 1
		.amdhsa_float_round_mode_32 0
		.amdhsa_float_round_mode_16_64 0
		.amdhsa_float_denorm_mode_32 3
		.amdhsa_float_denorm_mode_16_64 3
		.amdhsa_dx10_clamp 1
		.amdhsa_ieee_mode 1
		.amdhsa_fp16_overflow 0
		.amdhsa_tg_split 0
		.amdhsa_exception_fp_ieee_invalid_op 0
		.amdhsa_exception_fp_denorm_src 0
		.amdhsa_exception_fp_ieee_div_zero 0
		.amdhsa_exception_fp_ieee_overflow 0
		.amdhsa_exception_fp_ieee_underflow 0
		.amdhsa_exception_fp_ieee_inexact 0
		.amdhsa_exception_int_div_zero 0
	.end_amdhsa_kernel

amdhsa.kernels:
  - .agpr_count:     0
    .args:
      - .offset:         0
        .size:           232
        .value_kind:     by_value
      - .offset:         232
        .size:           4
        .value_kind:     hidden_block_count_x
      - .offset:         236
        .size:           4
        .value_kind:     hidden_block_count_y
      - .offset:         240
        .size:           4
        .value_kind:     hidden_block_count_z
      - .offset:         244
        .size:           2
        .value_kind:     hidden_group_size_x
      - .offset:         246
        .size:           2
        .value_kind:     hidden_group_size_y
      - .offset:         248
        .size:           2
        .value_kind:     hidden_group_size_z
      - .offset:         250
        .size:           2
        .value_kind:     hidden_remainder_x
      - .offset:         252
        .size:           2
        .value_kind:     hidden_remainder_y
      - .offset:         254
        .size:           2
        .value_kind:     hidden_remainder_z
      - .offset:         272
        .size:           8
        .value_kind:     hidden_global_offset_x
      - .offset:         280
        .size:           8
        .value_kind:     hidden_global_offset_y
      - .offset:         288
        .size:           8
        .value_kind:     hidden_global_offset_z
      - .offset:         296
        .size:           2
        .value_kind:     hidden_grid_dims
      - .offset:         320
        .size:           8
        .value_kind:     hidden_multigrid_sync_arg
    .group_segment_fixed_size: 81920
    .kernarg_segment_align: 8
    .kernarg_segment_size: 488
    .language:       OpenCL C
    .language_version:
      - 2
      - 0
    .max_flat_workgroup_size: 256
    .name:           _Z4mega6Params
    .private_segment_fixed_size: 0
    .sgpr_count:     108
    .sgpr_spill_count: 88
    .symbol:         _Z4mega6Params.kd
    .uniform_work_group_size: 1
    .uses_dynamic_stack: false
    .vgpr_count:     256
    .vgpr_spill_count: 0
    .wavefront_size: 64
